# input-projection epilogue: q/k/vg norm gains and row rstd parked in LDS once per tile instead of per-row-group global re-loads
# baseline (speedup 1.0000x reference)
.LBB0_78:
	v_readlane_b32 s54, v254, 46
	v_readlane_b32 s55, v254, 47
	s_waitcnt lgkmcnt(0)
	s_add_u32 s17, s52, s54
	s_addc_u32 s52, s53, s55
	v_readlane_b32 s53, v254, 26
	s_add_u32 s53, s14, s53
	v_readlane_b32 s54, v254, 25
	v_lshl_add_u32 v204, s34, 8, v241
	s_addc_u32 s54, s15, s54
	v_ashrrev_i32_e32 v205, 31, v204
	s_lshl_b64 s[10:11], s[10:11], 2
	v_lshl_add_u64 v[146:147], v[204:205], 4, s[14:15]
	s_mov_b32 s55, 0xa00000
	s_add_u32 s53, s53, s10
	v_add_co_u32_e32 v130, vcc, s55, v146
	s_addc_u32 s54, s54, s11
	s_lshl_b32 s10, s16, 8
	v_addc_co_u32_e32 v131, vcc, 0, v147, vcc
	s_ashr_i32 s11, s10, 31
	global_load_dwordx4 v[150:153], v[130:131], off
	s_lshl_b64 s[10:11], s[10:11], 2
	s_add_u32 s10, s53, s10
	v_readlane_b32 s53, v254, 11
	s_addc_u32 s11, s54, s11
	s_lshl_b32 s53, s53, 2
	s_add_u32 s10, s10, s53
	s_addc_u32 s11, s11, 0
	v_lshlrev_b32_e32 v0, 2, v184
	v_lshl_add_u64 v[130:131], s[10:11], 0, v[0:1]
	s_mov_b32 s10, 0xb05000
	v_add_co_u32_e32 v132, vcc, s10, v130
	s_mov_b64 s[10:11], 0xb05800
	s_nop 0
	v_addc_co_u32_e32 v133, vcc, 0, v131, vcc
	v_lshl_add_u64 v[130:131], v[130:131], 0, s[10:11]
	s_mov_b64 s[10:11], 0xa00000
	global_load_dwordx4 v[142:145], v[132:133], off offset:2048
	global_load_dwordx4 v[138:141], v[130:131], off offset:64
	global_load_dwordx4 v[134:137], v[130:131], off offset:512
	s_nop 0
	global_load_dwordx4 v[130:133], v[130:131], off offset:576
	v_lshl_add_u64 v[208:209], v[146:147], 0, s[10:11]
	v_mov_b32_e32 v210, v204
	global_load_dwordx4 v[166:169], v[208:209], off offset:256
	global_load_dwordx4 v[170:173], v[208:209], off offset:512
	global_load_dwordx4 v[212:215], v[208:209], off offset:768
	global_load_dwordx4 v[216:219], v[208:209], off offset:2048
	global_load_dwordx4 v[220:223], v[208:209], off offset:2304
	global_load_dwordx4 v[224:227], v[208:209], off offset:2560
	global_load_dwordx4 v[248:251], v[208:209], off offset:2816
	s_cmp_lg_u32 s16, 0
	s_cselect_b64 s[88:89], -1, 0
	s_cmp_gt_i32 s16, 4
	s_cselect_b64 s[80:81], -1, 0
	s_cmp_gt_u32 s16, 6
	s_cselect_b64 s[10:11], -1, 0
	v_writelane_b32 v254, s10, 60
	s_cmp_lg_u32 s16, 7
	v_lshlrev_b32_e32 v0, 2, v182
	v_writelane_b32 v254, s11, 61
	s_cselect_b64 s[10:11], -1, 0
	v_writelane_b32 v254, s10, 62
	v_lshlrev_b32_e32 v154, 1, v182
	v_mov_b32_e32 v155, v1
	v_writelane_b32 v254, s11, 63
	s_add_u32 s10, s14, 0x9000000
	s_addc_u32 s11, s15, 0
	v_writelane_b32 v255, s10, 0
	v_readlane_b32 s53, v254, 18
	v_mov_b32_e32 v199, v1
	v_writelane_b32 v255, s11, 1
	s_lshl_b32 s10, s53, 2
	s_add_u32 s10, s17, s10
	s_addc_u32 s11, s52, 0
	v_lshl_add_u64 v[202:203], s[10:11], 0, v[0:1]
	v_and_b32_e32 v230, 15, v238
	v_lshlrev_b32_e32 v230, 4, v230
	global_load_dwordx2 v[228:229], v230, s[10:11]
	global_load_dwordx2 v[232:233], v230, s[10:11] offset:8
	s_lshl_b32 s10, s53, 1
	s_add_u32 s10, s14, s10
	s_addc_u32 s11, s15, 0
	v_lshl_add_u64 v[206:207], s[10:11], 0, v[154:155]
	s_mov_b64 s[10:11], 0x8800000
	v_lshl_add_u64 v[200:201], v[206:207], 0, s[10:11]
	s_lshl_b32 s10, s16, 2
	v_readlane_b32 s11, v254, 12
	s_add_i32 s70, s11, s10
	s_lshl_b64 s[10:11], s[70:71], 21
	s_add_u32 s10, s14, s10
	s_addc_u32 s11, s15, s11
	s_add_u32 s54, s10, 0xb800000
	s_addc_u32 s55, s11, 0
	s_add_u32 s10, s12, 0x6000000
	s_addc_u32 s11, s13, 0
	v_writelane_b32 v255, s10, 2
	s_waitcnt vmcnt(0)
	v_readlane_b32 s17, v253, 45
	v_lshlrev_b32_e32 v243, 2, v241
	v_add_u32_e32 v243, 0x20800, v243
	s_and_b32 s17, s17, 3
	s_lshl_b32 s17, s17, 8
	s_add_i32 s17, s17, 0x20100
	v_add_f32_e32 v166, v166, v167
	v_add_f32_e32 v168, v168, v169
	v_add_f32_e32 v166, v166, v168
	v_fmamk_f32 v166, v166, 0x3a800000, v231
	v_add_f32_e32 v170, v170, v171
	v_add_f32_e32 v172, v172, v173
	v_add_f32_e32 v170, v170, v172
	v_fmamk_f32 v170, v170, 0x3a800000, v231
	v_add_f32_e32 v212, v212, v213
	v_add_f32_e32 v214, v214, v215
	v_add_f32_e32 v212, v212, v214
	v_fmamk_f32 v212, v212, 0x3a800000, v231
	v_add_f32_e32 v216, v216, v217
	v_add_f32_e32 v218, v218, v219
	v_add_f32_e32 v216, v216, v218
	v_fmamk_f32 v216, v216, 0x3a800000, v231
	v_add_f32_e32 v220, v220, v221
	v_add_f32_e32 v222, v222, v223
	v_add_f32_e32 v220, v220, v222
	v_fmamk_f32 v220, v220, 0x3a800000, v231
	v_add_f32_e32 v224, v224, v225
	v_add_f32_e32 v226, v226, v227
	v_add_f32_e32 v224, v224, v226
	v_fmamk_f32 v224, v224, 0x3a800000, v231
	v_add_f32_e32 v248, v248, v249
	v_add_f32_e32 v250, v250, v251
	v_add_f32_e32 v248, v248, v250
	v_fmamk_f32 v248, v248, 0x3a800000, v231
	v_rsq_f32_e32 v166, v166
	v_rsq_f32_e32 v170, v170
	v_rsq_f32_e32 v212, v212
	v_rsq_f32_e32 v216, v216
	v_rsq_f32_e32 v220, v220
	v_rsq_f32_e32 v224, v224
	v_rsq_f32_e32 v248, v248
	v_add_u32_e32 v235, s17, v230
	ds_write_b32 v243, v166 offset:64
	ds_write_b32 v243, v170 offset:128
	ds_write_b32 v243, v212 offset:192
	ds_write_b32 v243, v216 offset:512
	ds_write_b32 v243, v220 offset:576
	ds_write_b32 v243, v224 offset:640
	ds_write_b32 v243, v248 offset:704
	ds_write_b64 v235, v[228:229]
	ds_write_b64 v235, v[232:233] offset:8
	v_add_u32_e32 v193, s17, v0
	v_add_u32_e32 v192, 0x20000, v0
	s_cmp_lt_i32 s16, 3
	s_waitcnt vmcnt(0)
	v_mov_b32_e32 v156, v151
	v_writelane_b32 v255, s11, 3
	s_cselect_b64 s[10:11], -1, 0
	v_writelane_b32 v255, s10, 4
	s_cmp_gt_i32 s16, 2
	v_mov_b32_e32 v157, v152
	v_writelane_b32 v255, s11, 5
	s_cselect_b64 s[10:11], -1, 0
	s_and_b64 s[52:53], s[10:11], exec
	s_cselect_b32 s17, -3, -1
	s_cselect_b32 s52, s66, s64
	s_cselect_b32 s53, s67, s65
	s_add_i32 s17, s17, s16
	s_lshl_b32 s17, s17, 2
	v_readlane_b32 s64, v254, 43
	s_or_b32 s66, s17, s64
	v_readlane_b32 s64, v254, 48
	v_mov_b32_e32 v151, v153
	v_readlane_b32 s65, v254, 49
	s_add_u32 s64, s52, s64
	v_pk_add_f32 v[150:151], v[156:157], v[150:151]
	s_addc_u32 s65, s53, s65
	global_load_dwordx4 v[166:169], v230, s[64:65]
	s_ashr_i32 s67, s66, 31
	v_add_f32_e32 v150, v150, v151
	s_lshl_b64 s[52:53], s[66:67], 21
	v_fmamk_f32 v150, v150, 0x3a800000, v231
	s_add_u32 s14, s14, s52
	v_rsq_f32_e32 v162, v150
	s_addc_u32 s15, s15, s53
	v_lshl_add_u64 v[154:155], s[14:15], 0, v[154:155]
	s_mov_b64 s[52:53], 0x9800000
	v_lshl_add_u64 v[176:177], v[154:155], 0, s[52:53]
	v_lshl_add_u64 v[154:155], s[14:15], 0, v[198:199]
	s_mov_b64 s[14:15], 0xa800000
	s_add_u32 s52, s12, 0x4000000
	v_lshl_add_u64 v[174:175], v[154:155], 0, s[14:15]
	s_addc_u32 s53, s13, 0
	v_pk_fma_f32 v[152:153], v[32:33], v[162:163], v[144:145] op_sel_hi:[1,0,1]
	v_pk_fma_f32 v[150:151], v[30:31], v[162:163], v[142:143] op_sel_hi:[1,0,1]
	v_pk_fma_f32 v[156:157], v[28:29], v[162:163], v[140:141] op_sel_hi:[1,0,1]
	v_pk_fma_f32 v[154:155], v[26:27], v[162:163], v[138:139] op_sel_hi:[1,0,1]
	v_pk_fma_f32 v[160:161], v[24:25], v[162:163], v[136:137] op_sel_hi:[1,0,1]
	v_pk_fma_f32 v[158:159], v[22:23], v[162:163], v[134:135] op_sel_hi:[1,0,1]
	v_pk_fma_f32 v[164:165], v[16:17], v[162:163], v[132:133] op_sel_hi:[1,0,1]
	v_pk_fma_f32 v[162:163], v[14:15], v[162:163], v[130:131] op_sel_hi:[1,0,1]
	v_add_u32_e32 v235, 0x20000, v230
	s_waitcnt vmcnt(0)
	ds_write_b128 v235, v[166:169]
	s_waitcnt lgkmcnt(0)
	s_mov_b64 s[12:13], -1
	s_and_b64 vcc, exec, s[88:89]
	s_cbranch_vccz .LBB0_108
	s_and_b64 vcc, exec, s[80:81]
	s_cbranch_vccz .LBB0_97
	v_readlane_b32 s14, v254, 60
	v_readlane_b32 s15, v254, 61
	s_and_b64 vcc, exec, s[14:15]
	s_cbranch_vccz .LBB0_86
	v_readlane_b32 s14, v254, 62
	v_readlane_b32 s15, v254, 63
	s_andn2_b64 vcc, exec, s[14:15]
	v_mul_f32_e32 v222, 0x3d372713, v150
	v_mul_f32_e32 v220, 0x3d372713, v151
	v_mul_f32_e32 v218, 0x3d372713, v152
	v_mul_f32_e32 v216, 0x3d372713, v153
	v_mul_f32_e32 v221, 0x3d372713, v154
	v_mul_f32_e32 v219, 0x3d372713, v155
	v_mul_f32_e32 v217, 0x3d372713, v156
	v_mul_f32_e32 v215, 0x3d372713, v157
	v_mul_f32_e32 v214, 0x3d372713, v158
	v_mul_f32_e32 v212, 0x3d372713, v159
	v_mul_f32_e32 v199, 0x3d372713, v160
	v_mul_f32_e32 v173, 0x3d372713, v161
	v_mul_f32_e32 v213, 0x3d372713, v162
	v_mul_f32_e32 v205, 0x3d372713, v163
	v_mul_f32_e32 v191, 0x3d372713, v164
	v_mul_f32_e32 v172, 0x3d372713, v165
	s_cbranch_vccnz .LBB0_83
	v_mul_f32_e32 v167, v152, v218
	v_fma_f32 v167, v152, v167, v152
	v_mul_f32_e32 v167, 0x3f4c422a, v167
	v_add_f32_e32 v167, v167, v167
	v_mul_f32_e32 v167, 0xbfb8aa3b, v167
	v_exp_f32_e32 v167, v167
	v_mul_f32_e32 v166, v150, v222
	v_fma_f32 v166, v150, v166, v150
	v_mul_f32_e32 v166, 0x3f4c422a, v166
	v_add_f32_e32 v167, 1.0, v167
	v_rcp_f32_e32 v167, v167
	v_add_f32_e32 v166, v166, v166
	v_mul_f32_e32 v166, 0xbfb8aa3b, v166
	v_exp_f32_e32 v166, v166
	v_mul_f32_e32 v224, v152, v167
	v_mul_f32_e32 v167, v153, v216
	v_fma_f32 v167, v153, v167, v153
	v_mul_f32_e32 v167, 0x3f4c422a, v167
	v_add_f32_e32 v167, v167, v167
	v_mul_f32_e32 v167, 0xbfb8aa3b, v167
	v_exp_f32_e32 v167, v167
	v_add_f32_e32 v166, 1.0, v166
	v_rcp_f32_e32 v166, v166
	v_readlane_b32 s12, v255, 0
	v_add_f32_e32 v167, 1.0, v167
	v_rcp_f32_e32 v167, v167
	v_mul_f32_e32 v211, v150, v166
	v_mul_f32_e32 v166, v151, v220
	v_fma_f32 v166, v151, v166, v151
	v_mul_f32_e32 v225, v153, v167
	v_mul_f32_e32 v167, v154, v221
	v_fma_f32 v167, v154, v167, v154
	v_mul_f32_e32 v167, 0x3f4c422a, v167
	v_add_f32_e32 v167, v167, v167
	v_mul_f32_e32 v167, 0xbfb8aa3b, v167
	v_exp_f32_e32 v167, v167
	v_mul_f32_e32 v166, 0x3f4c422a, v166
	v_add_f32_e32 v166, v166, v166
	v_mul_f32_e32 v166, 0xbfb8aa3b, v166
	v_add_f32_e32 v167, 1.0, v167
	v_rcp_f32_e32 v167, v167
	v_exp_f32_e32 v166, v166
	v_readlane_b32 s13, v255, 1
	v_lshlrev_b32_e32 v168, 6, v210
	v_mul_f32_e32 v226, v154, v167
	v_mul_f32_e32 v167, v155, v219
	v_fma_f32 v167, v155, v167, v155
	v_mul_f32_e32 v167, 0x3f4c422a, v167
	v_add_f32_e32 v167, v167, v167
	v_mul_f32_e32 v167, 0xbfb8aa3b, v167
	v_exp_f32_e32 v167, v167
	v_add_f32_e32 v166, 1.0, v166
	v_rcp_f32_e32 v166, v166
	v_and_b32_e32 v168, 0x1c00, v168
	v_add_f32_e32 v167, 1.0, v167
	v_rcp_f32_e32 v167, v167
	v_mul_f32_e32 v223, v151, v166
	v_mul_f32_e32 v166, v223, v223
	v_fmac_f32_e32 v166, v211, v211
	v_mul_f32_e32 v227, v155, v167
	v_mul_f32_e32 v167, v156, v217
	v_fma_f32 v167, v156, v167, v156
	v_mul_f32_e32 v167, 0x3f4c422a, v167
	v_add_f32_e32 v167, v167, v167
	v_mul_f32_e32 v167, 0xbfb8aa3b, v167
	v_exp_f32_e32 v167, v167
	v_fmac_f32_e32 v166, v224, v224
	v_fmac_f32_e32 v166, v225, v225
	v_fmac_f32_e32 v166, v226, v226
	v_add_f32_e32 v167, 1.0, v167
	v_rcp_f32_e32 v167, v167
	v_fmac_f32_e32 v166, v227, v227
	v_mov_b32_e32 v169, v1
	v_mul_f32_e32 v228, v156, v167
	v_mul_f32_e32 v167, v157, v215
	v_fma_f32 v167, v157, v167, v157
	v_mul_f32_e32 v167, 0x3f4c422a, v167
	v_add_f32_e32 v167, v167, v167
	v_mul_f32_e32 v167, 0xbfb8aa3b, v167
	v_exp_f32_e32 v167, v167
	v_fmac_f32_e32 v166, v228, v228
	v_add_f32_e32 v167, 1.0, v167
	v_rcp_f32_e32 v167, v167
	s_nop 0
	v_mul_f32_e32 v229, v157, v167
	v_mul_f32_e32 v167, v158, v214
	v_fma_f32 v167, v158, v167, v158
	v_mul_f32_e32 v167, 0x3f4c422a, v167
	v_add_f32_e32 v167, v167, v167
	v_mul_f32_e32 v167, 0xbfb8aa3b, v167
	v_exp_f32_e32 v167, v167
	v_fmac_f32_e32 v166, v229, v229
	v_add_f32_e32 v167, 1.0, v167
	v_rcp_f32_e32 v167, v167
	s_nop 0
	v_mul_f32_e32 v248, v158, v167
	v_mul_f32_e32 v167, v159, v212
	v_fma_f32 v167, v159, v167, v159
	v_mul_f32_e32 v167, 0x3f4c422a, v167
	v_add_f32_e32 v167, v167, v167
	v_mul_f32_e32 v167, 0xbfb8aa3b, v167
	v_exp_f32_e32 v167, v167
	v_fmac_f32_e32 v166, v248, v248
	v_add_f32_e32 v167, 1.0, v167
	v_rcp_f32_e32 v167, v167
	s_nop 0
	v_mul_f32_e32 v230, v159, v167
	v_mul_f32_e32 v167, v160, v199
	v_fma_f32 v167, v160, v167, v160
	v_mul_f32_e32 v167, 0x3f4c422a, v167
	v_add_f32_e32 v167, v167, v167
	v_mul_f32_e32 v167, 0xbfb8aa3b, v167
	v_exp_f32_e32 v167, v167
	v_fmac_f32_e32 v166, v230, v230
	v_add_f32_e32 v167, 1.0, v167
	v_rcp_f32_e32 v167, v167
	s_nop 0
	v_mul_f32_e32 v187, v160, v167
	v_mul_f32_e32 v167, v161, v173
	v_fma_f32 v167, v161, v167, v161
	v_mul_f32_e32 v167, 0x3f4c422a, v167
	v_add_f32_e32 v167, v167, v167
	v_mul_f32_e32 v167, 0xbfb8aa3b, v167
	v_exp_f32_e32 v167, v167
	v_fmac_f32_e32 v166, v187, v187
	v_add_f32_e32 v167, 1.0, v167
	v_rcp_f32_e32 v167, v167
	s_nop 0
	v_mul_f32_e32 v235, v161, v167
	v_mul_f32_e32 v167, v162, v213
	v_fma_f32 v167, v162, v167, v162
	v_mul_f32_e32 v167, 0x3f4c422a, v167
	v_add_f32_e32 v167, v167, v167
	v_mul_f32_e32 v167, 0xbfb8aa3b, v167
	v_exp_f32_e32 v167, v167
	v_fmac_f32_e32 v166, v235, v235
	v_add_f32_e32 v167, 1.0, v167
	v_rcp_f32_e32 v167, v167
	s_nop 0
	v_mul_f32_e32 v233, v162, v167
	v_mul_f32_e32 v167, v163, v205
	v_fma_f32 v167, v163, v167, v163
	v_mul_f32_e32 v167, 0x3f4c422a, v167
	v_add_f32_e32 v167, v167, v167
	v_mul_f32_e32 v167, 0xbfb8aa3b, v167
	v_exp_f32_e32 v167, v167
	v_fmac_f32_e32 v166, v233, v233
	v_add_f32_e32 v167, 1.0, v167
	v_rcp_f32_e32 v167, v167
	s_nop 0
	v_mul_f32_e32 v232, v163, v167
	v_mul_f32_e32 v167, v164, v191
	v_fma_f32 v167, v164, v167, v164
	v_mul_f32_e32 v167, 0x3f4c422a, v167
	v_add_f32_e32 v167, v167, v167
	v_mul_f32_e32 v167, 0xbfb8aa3b, v167
	v_exp_f32_e32 v167, v167
	v_fmac_f32_e32 v166, v232, v232
	v_add_f32_e32 v167, 1.0, v167
	v_rcp_f32_e32 v167, v167
	s_nop 0
	v_mul_f32_e32 v250, v164, v167
	v_mul_f32_e32 v167, v165, v172
	v_fma_f32 v167, v165, v167, v165
	v_mul_f32_e32 v167, 0x3f4c422a, v167
	v_add_f32_e32 v167, v167, v167
	v_mul_f32_e32 v167, 0xbfb8aa3b, v167
	v_exp_f32_e32 v167, v167
	v_fmac_f32_e32 v166, v250, v250
	v_add_f32_e32 v167, 1.0, v167
	v_rcp_f32_e32 v167, v167
	s_nop 0
	v_mul_f32_e32 v249, v165, v167
	v_fmac_f32_e32 v166, v249, v249
	ds_bpermute_b32 v167, v244, v166
	s_waitcnt lgkmcnt(0)
	v_add_f32_e32 v166, v166, v167
	ds_bpermute_b32 v167, v245, v166
	s_waitcnt lgkmcnt(0)
	v_add_f32_e32 v166, v166, v167
	v_fmamk_f32 v166, v166, 0x3c800000, v231
	v_rsq_f32_e32 v251, v166
	v_ashrrev_i32_e32 v166, 7, v210
	v_ashrrev_i32_e32 v167, 31, v166
	v_lshlrev_b64 v[166:167], 16, v[166:167]
	v_lshl_add_u64 v[166:167], s[12:13], 0, v[166:167]
	v_lshl_add_u64 v[166:167], v[166:167], 0, v[168:169]
	v_and_b32_e32 v168, 8, v210
	v_lshlrev_b32_e32 v168, 1, v168
	v_lshl_add_u64 v[166:167], v[166:167], 0, v[168:169]
	v_and_b32_e32 v168, 7, v210
	v_lshlrev_b32_e32 v168, 1, v168
	v_readlane_b32 s12, v254, 15
	v_lshl_add_u64 v[166:167], v[166:167], 0, v[168:169]
	s_lshl_b32 s12, s12, 1
	s_mov_b32 s13, s71
	v_lshl_add_u64 v[166:167], v[166:167], 0, s[12:13]
	v_lshlrev_b32_e32 v168, 1, v186
	v_lshl_add_u64 v[170:171], v[166:167], 0, v[168:169]
	ds_read_b128 v[166:169], v193
	v_mul_f32_e32 v211, v211, v251
	s_movk_i32 s12, 0x2000
	s_waitcnt lgkmcnt(0)
	v_mul_f32_e32 v166, v166, v211
	v_cvt_pk_bf16_f32 v166, v166, s0
	global_store_short v[170:171], v166, off
	v_mul_f32_e32 v166, v223, v251
	v_mul_f32_e32 v166, v167, v166
	v_cvt_pk_bf16_f32 v166, v166, s0
	global_store_short v[170:171], v166, off offset:32
	v_mul_f32_e32 v166, v224, v251
	v_mul_f32_e32 v166, v168, v166
	v_cvt_pk_bf16_f32 v166, v166, s0
	global_store_short v[170:171], v166, off offset:64
	v_mul_f32_e32 v166, v225, v251
	v_mul_f32_e32 v166, v169, v166
	v_cvt_pk_bf16_f32 v166, v166, s0
	global_store_short v[170:171], v166, off offset:96
	ds_read_b128 v[166:169], v193 offset:16
	v_mul_f32_e32 v211, v226, v251
	s_waitcnt lgkmcnt(0)
	v_mul_f32_e32 v166, v211, v166
	v_cvt_pk_bf16_f32 v166, v166, s0
	global_store_short v[170:171], v166, off offset:128
	v_mul_f32_e32 v166, v227, v251
	v_mul_f32_e32 v166, v166, v167
	v_cvt_pk_bf16_f32 v166, v166, s0
	global_store_short v[170:171], v166, off offset:160
	v_mul_f32_e32 v166, v228, v251
	v_mul_f32_e32 v166, v166, v168
	v_cvt_pk_bf16_f32 v166, v166, s0
	global_store_short v[170:171], v166, off offset:192
	v_mul_f32_e32 v166, v229, v251
	v_mul_f32_e32 v166, v166, v169
	v_cvt_pk_bf16_f32 v166, v166, s0
	global_store_short v[170:171], v166, off offset:224
	ds_read_b128 v[166:169], v193 offset:128
	v_mul_f32_e32 v211, v248, v251
	v_add_co_u32_e32 v170, vcc, s12, v170
	s_mov_b64 s[12:13], 0
	s_nop 0
	v_addc_co_u32_e32 v171, vcc, 0, v171, vcc
	s_waitcnt lgkmcnt(0)
	v_mul_f32_e32 v166, v211, v166
	v_cvt_pk_bf16_f32 v166, v166, s0
	global_store_short v[170:171], v166, off
	v_mul_f32_e32 v166, v230, v251
	v_mul_f32_e32 v166, v166, v167
	v_cvt_pk_bf16_f32 v166, v166, s0
	global_store_short v[170:171], v166, off offset:32
	v_mul_f32_e32 v166, v187, v251
	v_mul_f32_e32 v166, v166, v168
	v_cvt_pk_bf16_f32 v166, v166, s0
	global_store_short v[170:171], v166, off offset:64
	v_mul_f32_e32 v166, v235, v251
	v_mul_f32_e32 v166, v166, v169
	v_cvt_pk_bf16_f32 v166, v166, s0
	global_store_short v[170:171], v166, off offset:96
	ds_read_b128 v[166:169], v193 offset:144
	v_mul_f32_e32 v187, v233, v251
	s_waitcnt lgkmcnt(0)
	v_mul_f32_e32 v166, v187, v166
	v_cvt_pk_bf16_f32 v166, v166, s0
	global_store_short v[170:171], v166, off offset:128
	v_mul_f32_e32 v166, v232, v251
	v_mul_f32_e32 v166, v166, v167
	v_cvt_pk_bf16_f32 v166, v166, s0
	global_store_short v[170:171], v166, off offset:160
	v_mul_f32_e32 v166, v250, v251
	v_mul_f32_e32 v166, v166, v168
	v_cvt_pk_bf16_f32 v166, v166, s0
	global_store_short v[170:171], v166, off offset:192
	v_mul_f32_e32 v166, v249, v251
	v_mul_f32_e32 v166, v166, v169
	v_cvt_pk_bf16_f32 v166, v166, s0
	global_store_short v[170:171], v166, off offset:224

.LBB0_102:
	s_waitcnt lgkmcnt(0)
	v_add_f32_e32 v166, v166, v167
	v_fmamk_f32 v166, v166, 0x3c800000, v231
	v_rsq_f32_e32 v166, v166
	s_movk_i32 s12, 0x2000
	v_cmp_gt_i32_e32 vcc, s12, v210
	s_and_b64 s[12:13], s[10:11], vcc
	v_mul_f32_e32 v167, 0x3e38aa3b, v166
	v_cndmask_b32_e64 v216, v167, v166, s[10:11]
	v_ashrrev_i32_e32 v166, 8, v210
	v_ashrrev_i32_e32 v167, 31, v166
	v_lshlrev_b64 v[166:167], 20, v[166:167]
	v_readlane_b32 vcc_lo, v254, 27
	v_lshl_add_u64 v[166:167], s[52:53], 0, v[166:167]
	v_readlane_b32 vcc_hi, v254, 28
	s_lshl_b64 s[14:15], s[66:67], 16
	v_lshlrev_b32_e32 v168, 8, v210
	v_lshl_add_u64 v[166:167], v[166:167], 0, vcc
	v_lshl_add_u64 v[166:167], v[166:167], 0, s[14:15]
	v_and_b32_e32 v168, 0xff00, v168
	v_mov_b32_e32 v169, v1
	v_lshl_add_u64 v[214:215], v[166:167], 0, v[168:169]
	ds_read_b128 v[170:173], v192 offset:16
	ds_read_b128 v[166:169], v192
	v_pk_mul_f32 v[218:219], v[150:151], v[216:217] op_sel_hi:[1,0]
	v_pk_mul_f32 v[220:221], v[152:153], v[216:217] op_sel_hi:[1,0]
	s_waitcnt lgkmcnt(0)
	v_pk_mul_f32 v[166:167], v[218:219], v[166:167]
	v_pk_mul_f32 v[168:169], v[220:221], v[168:169]
	v_pk_mul_f32 v[218:219], v[154:155], v[216:217] op_sel_hi:[1,0]
	v_pk_mul_f32 v[220:221], v[156:157], v[216:217] op_sel_hi:[1,0]
	v_pk_mul_f32 v[170:171], v[218:219], v[170:171]
	v_pk_mul_f32 v[172:173], v[220:221], v[172:173]
	v_cvt_pk_bf16_f32 v218, v166, v167
	v_cvt_pk_bf16_f32 v219, v168, v169
	v_cvt_pk_bf16_f32 v220, v170, v171
	v_cvt_pk_bf16_f32 v221, v172, v173
	global_store_dwordx4 v[212:213], v[218:221], off
	s_and_saveexec_b64 s[14:15], s[12:13]
	s_cbranch_execz .LBB0_104
	v_lshl_add_u64 v[218:219], v[214:215], 0, v[0:1]
	global_store_dwordx4 v[218:219], v[166:169], off nt
	global_store_dwordx4 v[218:219], v[170:173], off offset:16 nt
.LBB0_104:
	s_or_b64 exec, exec, s[14:15]
	s_nop 0
	ds_read_b128 v[166:169], v192 offset:128
	s_nop 0
	ds_read_b128 v[170:173], v192 offset:144
	v_mov_b32_e32 v217, v216
	v_mov_b32_e32 v218, v216
	v_mov_b32_e32 v219, v216
	s_and_b64 s[14:15], s[10:11], exec
	v_pk_mul_f32 v[220:221], v[160:161], v[218:219]
	v_pk_mul_f32 v[222:223], v[158:159], v[216:217]
	v_pk_mul_f32 v[218:219], v[164:165], v[218:219]
	v_pk_mul_f32 v[216:217], v[162:163], v[216:217]
	s_mov_b32 s15, s71
	s_cselect_b32 s14, 0x800, 64
	v_lshl_add_u64 v[212:213], v[212:213], 0, s[14:15]
	s_waitcnt lgkmcnt(1)
	v_pk_mul_f32 v[168:169], v[220:221], v[168:169]
	v_pk_mul_f32 v[166:167], v[222:223], v[166:167]
	s_waitcnt lgkmcnt(0)
	v_pk_mul_f32 v[172:173], v[218:219], v[172:173]
	v_pk_mul_f32 v[170:171], v[216:217], v[170:171]
	v_cvt_pk_bf16_f32 v216, v166, v167
	v_cvt_pk_bf16_f32 v217, v168, v169
	v_cvt_pk_bf16_f32 v218, v170, v171
	v_cvt_pk_bf16_f32 v219, v172, v173
	global_store_dwordx4 v[212:213], v[216:219], off
	s_and_saveexec_b64 s[14:15], s[12:13]
	s_cbranch_execz .LBB0_106
	v_lshl_add_u64 v[212:213], v[214:215], 0, v[0:1]
	global_store_dwordx4 v[212:213], v[166:169], off offset:128 nt
	global_store_dwordx4 v[212:213], v[170:173], off offset:144 nt

.LBB0_110:
	v_or_b32_e32 v210, 16, v204
	v_cndmask_b32_e64 v166, 0, 1, s[88:89]
	ds_read_b32 v162, v243 offset:64
	s_waitcnt lgkmcnt(0)
	v_cmp_ne_u32_e64 s[14:15], 1, v166
	v_cndmask_b32_e64 v166, 0, 1, s[80:81]
	s_andn2_b64 vcc, exec, s[88:89]
	v_pk_fma_f32 v[148:149], v[20:21], v[162:163], v[144:145] op_sel_hi:[1,0,1]
	v_pk_fma_f32 v[146:147], v[18:19], v[162:163], v[142:143] op_sel_hi:[1,0,1]
	v_pk_fma_f32 v[156:157], v[12:13], v[162:163], v[140:141] op_sel_hi:[1,0,1]
	v_pk_fma_f32 v[154:155], v[10:11], v[162:163], v[138:139] op_sel_hi:[1,0,1]
	v_pk_fma_f32 v[160:161], v[8:9], v[162:163], v[136:137] op_sel_hi:[1,0,1]
	v_pk_fma_f32 v[158:159], v[6:7], v[162:163], v[134:135] op_sel_hi:[1,0,1]
	v_pk_fma_f32 v[164:165], v[4:5], v[162:163], v[132:133] op_sel_hi:[1,0,1]
	v_pk_fma_f32 v[162:163], v[2:3], v[162:163], v[130:131] op_sel_hi:[1,0,1]
	v_cmp_ne_u32_e64 s[12:13], 1, v166
	s_cbranch_vccnz .LBB0_326
	s_and_b64 vcc, exec, s[12:13]
	s_mov_b64 s[80:81], -1
	s_cbranch_vccnz .LBB0_129
	v_readlane_b32 s80, v254, 60
	v_readlane_b32 s81, v254, 61
	s_andn2_b64 vcc, exec, s[80:81]
	s_mov_b64 s[80:81], -1
	s_cbranch_vccnz .LBB0_118
	v_readlane_b32 s88, v254, 62
	v_readlane_b32 s89, v254, 63
	s_andn2_b64 vcc, exec, s[88:89]
	v_mul_f32_e32 v222, 0x3d372713, v146
	v_mul_f32_e32 v220, 0x3d372713, v147
	v_mul_f32_e32 v218, 0x3d372713, v148
	v_mul_f32_e32 v216, 0x3d372713, v149
	v_mul_f32_e32 v221, 0x3d372713, v154
	v_mul_f32_e32 v219, 0x3d372713, v155
	v_mul_f32_e32 v217, 0x3d372713, v156
	v_mul_f32_e32 v215, 0x3d372713, v157
	v_mul_f32_e32 v214, 0x3d372713, v158
	v_mul_f32_e32 v212, 0x3d372713, v159
	v_mul_f32_e32 v199, 0x3d372713, v160
	v_mul_f32_e32 v173, 0x3d372713, v161
	v_mul_f32_e32 v213, 0x3d372713, v162
	v_mul_f32_e32 v205, 0x3d372713, v163
	v_mul_f32_e32 v191, 0x3d372713, v164
	v_mul_f32_e32 v172, 0x3d372713, v165
	s_cbranch_vccnz .LBB0_115
	v_mul_f32_e32 v167, v148, v218
	v_fma_f32 v167, v148, v167, v148
	v_mul_f32_e32 v167, 0x3f4c422a, v167
	v_add_f32_e32 v167, v167, v167
	v_mul_f32_e32 v167, 0xbfb8aa3b, v167
	v_exp_f32_e32 v167, v167
	v_mul_f32_e32 v166, v146, v222
	v_fma_f32 v166, v146, v166, v146
	v_mul_f32_e32 v166, 0x3f4c422a, v166
	v_add_f32_e32 v167, 1.0, v167
	v_rcp_f32_e32 v167, v167
	v_add_f32_e32 v166, v166, v166
	v_mul_f32_e32 v166, 0xbfb8aa3b, v166
	v_exp_f32_e32 v166, v166
	v_mul_f32_e32 v224, v148, v167
	v_mul_f32_e32 v167, v149, v216
	v_fma_f32 v167, v149, v167, v149
	v_mul_f32_e32 v167, 0x3f4c422a, v167
	v_add_f32_e32 v167, v167, v167
	v_mul_f32_e32 v167, 0xbfb8aa3b, v167
	v_exp_f32_e32 v167, v167
	v_add_f32_e32 v166, 1.0, v166
	v_rcp_f32_e32 v166, v166
	v_readlane_b32 s80, v255, 0
	v_add_f32_e32 v167, 1.0, v167
	v_rcp_f32_e32 v167, v167
	v_mul_f32_e32 v211, v146, v166
	v_mul_f32_e32 v166, v147, v220
	v_fma_f32 v166, v147, v166, v147
	v_mul_f32_e32 v225, v149, v167
	v_mul_f32_e32 v167, v154, v221
	v_fma_f32 v167, v154, v167, v154
	v_mul_f32_e32 v167, 0x3f4c422a, v167
	v_add_f32_e32 v167, v167, v167
	v_mul_f32_e32 v167, 0xbfb8aa3b, v167
	v_exp_f32_e32 v167, v167
	v_mul_f32_e32 v166, 0x3f4c422a, v166
	v_add_f32_e32 v166, v166, v166
	v_mul_f32_e32 v166, 0xbfb8aa3b, v166
	v_add_f32_e32 v167, 1.0, v167
	v_rcp_f32_e32 v167, v167
	v_exp_f32_e32 v166, v166
	v_readlane_b32 s81, v255, 1
	v_lshlrev_b32_e32 v168, 6, v210
	v_mul_f32_e32 v226, v154, v167
	v_mul_f32_e32 v167, v155, v219
	v_fma_f32 v167, v155, v167, v155
	v_mul_f32_e32 v167, 0x3f4c422a, v167
	v_add_f32_e32 v167, v167, v167
	v_mul_f32_e32 v167, 0xbfb8aa3b, v167
	v_exp_f32_e32 v167, v167
	v_add_f32_e32 v166, 1.0, v166
	v_rcp_f32_e32 v166, v166
	v_and_b32_e32 v168, 0x1c00, v168
	v_add_f32_e32 v167, 1.0, v167
	v_rcp_f32_e32 v167, v167
	v_mul_f32_e32 v223, v147, v166
	v_mul_f32_e32 v166, v223, v223
	v_fmac_f32_e32 v166, v211, v211
	v_mul_f32_e32 v227, v155, v167
	v_mul_f32_e32 v167, v156, v217
	v_fma_f32 v167, v156, v167, v156
	v_mul_f32_e32 v167, 0x3f4c422a, v167
	v_add_f32_e32 v167, v167, v167
	v_mul_f32_e32 v167, 0xbfb8aa3b, v167
	v_exp_f32_e32 v167, v167
	v_fmac_f32_e32 v166, v224, v224
	v_fmac_f32_e32 v166, v225, v225
	v_fmac_f32_e32 v166, v226, v226
	v_add_f32_e32 v167, 1.0, v167
	v_rcp_f32_e32 v167, v167
	v_fmac_f32_e32 v166, v227, v227
	v_mov_b32_e32 v169, v1
	v_readlane_b32 s17, v254, 15
	v_mul_f32_e32 v228, v156, v167
	v_mul_f32_e32 v167, v157, v215
	v_fma_f32 v167, v157, v167, v157
	v_mul_f32_e32 v167, 0x3f4c422a, v167
	v_add_f32_e32 v167, v167, v167
	v_mul_f32_e32 v167, 0xbfb8aa3b, v167
	v_exp_f32_e32 v167, v167
	v_fmac_f32_e32 v166, v228, v228
	v_add_f32_e32 v167, 1.0, v167
	v_rcp_f32_e32 v167, v167
	s_nop 0
	v_mul_f32_e32 v229, v157, v167
	v_mul_f32_e32 v167, v158, v214
	v_fma_f32 v167, v158, v167, v158
	v_mul_f32_e32 v167, 0x3f4c422a, v167
	v_add_f32_e32 v167, v167, v167
	v_mul_f32_e32 v167, 0xbfb8aa3b, v167
	v_exp_f32_e32 v167, v167
	v_fmac_f32_e32 v166, v229, v229
	v_add_f32_e32 v167, 1.0, v167
	v_rcp_f32_e32 v167, v167
	s_nop 0
	v_mul_f32_e32 v248, v158, v167
	v_mul_f32_e32 v167, v159, v212
	v_fma_f32 v167, v159, v167, v159
	v_mul_f32_e32 v167, 0x3f4c422a, v167
	v_add_f32_e32 v167, v167, v167
	v_mul_f32_e32 v167, 0xbfb8aa3b, v167
	v_exp_f32_e32 v167, v167
	v_fmac_f32_e32 v166, v248, v248
	v_add_f32_e32 v167, 1.0, v167
	v_rcp_f32_e32 v167, v167
	s_nop 0
	v_mul_f32_e32 v230, v159, v167
	v_mul_f32_e32 v167, v160, v199
	v_fma_f32 v167, v160, v167, v160
	v_mul_f32_e32 v167, 0x3f4c422a, v167
	v_add_f32_e32 v167, v167, v167
	v_mul_f32_e32 v167, 0xbfb8aa3b, v167
	v_exp_f32_e32 v167, v167
	v_fmac_f32_e32 v166, v230, v230
	v_add_f32_e32 v167, 1.0, v167
	v_rcp_f32_e32 v167, v167
	s_nop 0
	v_mul_f32_e32 v187, v160, v167
	v_mul_f32_e32 v167, v161, v173
	v_fma_f32 v167, v161, v167, v161
	v_mul_f32_e32 v167, 0x3f4c422a, v167
	v_add_f32_e32 v167, v167, v167
	v_mul_f32_e32 v167, 0xbfb8aa3b, v167
	v_exp_f32_e32 v167, v167
	v_fmac_f32_e32 v166, v187, v187
	v_add_f32_e32 v167, 1.0, v167
	v_rcp_f32_e32 v167, v167
	s_nop 0
	v_mul_f32_e32 v235, v161, v167
	v_mul_f32_e32 v167, v162, v213
	v_fma_f32 v167, v162, v167, v162
	v_mul_f32_e32 v167, 0x3f4c422a, v167
	v_add_f32_e32 v167, v167, v167
	v_mul_f32_e32 v167, 0xbfb8aa3b, v167
	v_exp_f32_e32 v167, v167
	v_fmac_f32_e32 v166, v235, v235
	v_add_f32_e32 v167, 1.0, v167
	v_rcp_f32_e32 v167, v167
	s_nop 0
	v_mul_f32_e32 v233, v162, v167
	v_mul_f32_e32 v167, v163, v205
	v_fma_f32 v167, v163, v167, v163
	v_mul_f32_e32 v167, 0x3f4c422a, v167
	v_add_f32_e32 v167, v167, v167
	v_mul_f32_e32 v167, 0xbfb8aa3b, v167
	v_exp_f32_e32 v167, v167
	v_fmac_f32_e32 v166, v233, v233
	v_add_f32_e32 v167, 1.0, v167
	v_rcp_f32_e32 v167, v167
	s_nop 0
	v_mul_f32_e32 v232, v163, v167
	v_mul_f32_e32 v167, v164, v191
	v_fma_f32 v167, v164, v167, v164
	v_mul_f32_e32 v167, 0x3f4c422a, v167
	v_add_f32_e32 v167, v167, v167
	v_mul_f32_e32 v167, 0xbfb8aa3b, v167
	v_exp_f32_e32 v167, v167
	v_fmac_f32_e32 v166, v232, v232
	v_add_f32_e32 v167, 1.0, v167
	v_rcp_f32_e32 v167, v167
	s_nop 0
	v_mul_f32_e32 v250, v164, v167
	v_mul_f32_e32 v167, v165, v172
	v_fma_f32 v167, v165, v167, v165
	v_mul_f32_e32 v167, 0x3f4c422a, v167
	v_add_f32_e32 v167, v167, v167
	v_mul_f32_e32 v167, 0xbfb8aa3b, v167
	v_exp_f32_e32 v167, v167
	v_fmac_f32_e32 v166, v250, v250
	v_add_f32_e32 v167, 1.0, v167
	v_rcp_f32_e32 v167, v167
	s_nop 0
	v_mul_f32_e32 v249, v165, v167
	v_fmac_f32_e32 v166, v249, v249
	ds_bpermute_b32 v167, v244, v166
	s_waitcnt lgkmcnt(0)
	v_add_f32_e32 v166, v166, v167
	ds_bpermute_b32 v167, v245, v166
	s_waitcnt lgkmcnt(0)
	v_add_f32_e32 v166, v166, v167
	v_fmamk_f32 v166, v166, 0x3c800000, v231
	v_rsq_f32_e32 v251, v166
	v_ashrrev_i32_e32 v166, 7, v210
	v_ashrrev_i32_e32 v167, 31, v166
	v_lshlrev_b64 v[166:167], 16, v[166:167]
	v_lshl_add_u64 v[166:167], s[80:81], 0, v[166:167]
	v_lshl_add_u64 v[166:167], v[166:167], 0, v[168:169]
	v_and_b32_e32 v168, 8, v210
	v_lshlrev_b32_e32 v168, 1, v168
	v_lshl_add_u64 v[166:167], v[166:167], 0, v[168:169]
	v_and_b32_e32 v168, 7, v210
	v_lshlrev_b32_e32 v168, 1, v168
	v_lshl_add_u64 v[166:167], v[166:167], 0, v[168:169]
	s_lshl_b32 s80, s17, 1
	s_mov_b32 s81, s71
	v_lshl_add_u64 v[166:167], v[166:167], 0, s[80:81]
	v_lshlrev_b32_e32 v168, 1, v186
	v_lshl_add_u64 v[170:171], v[166:167], 0, v[168:169]
	ds_read_b128 v[166:169], v193
	v_mul_f32_e32 v211, v211, v251
	s_movk_i32 s17, 0x2000
	s_mov_b64 s[80:81], 0
	s_waitcnt lgkmcnt(0)
	v_mul_f32_e32 v166, v166, v211
	v_cvt_pk_bf16_f32 v166, v166, s0
	global_store_short v[170:171], v166, off
	v_mul_f32_e32 v166, v223, v251
	v_mul_f32_e32 v166, v167, v166
	v_cvt_pk_bf16_f32 v166, v166, s0
	global_store_short v[170:171], v166, off offset:32
	v_mul_f32_e32 v166, v224, v251
	v_mul_f32_e32 v166, v168, v166
	v_cvt_pk_bf16_f32 v166, v166, s0
	global_store_short v[170:171], v166, off offset:64
	v_mul_f32_e32 v166, v225, v251
	v_mul_f32_e32 v166, v169, v166
	v_cvt_pk_bf16_f32 v166, v166, s0
	global_store_short v[170:171], v166, off offset:96
	ds_read_b128 v[166:169], v193 offset:16
	v_mul_f32_e32 v211, v226, v251
	s_waitcnt lgkmcnt(0)
	v_mul_f32_e32 v166, v211, v166
	v_cvt_pk_bf16_f32 v166, v166, s0
	global_store_short v[170:171], v166, off offset:128
	v_mul_f32_e32 v166, v227, v251
	v_mul_f32_e32 v166, v166, v167
	v_cvt_pk_bf16_f32 v166, v166, s0
	global_store_short v[170:171], v166, off offset:160
	v_mul_f32_e32 v166, v228, v251
	v_mul_f32_e32 v166, v166, v168
	v_cvt_pk_bf16_f32 v166, v166, s0
	global_store_short v[170:171], v166, off offset:192
	v_mul_f32_e32 v166, v229, v251
	v_mul_f32_e32 v166, v166, v169
	v_cvt_pk_bf16_f32 v166, v166, s0
	global_store_short v[170:171], v166, off offset:224
	ds_read_b128 v[166:169], v193 offset:128
	v_mul_f32_e32 v211, v248, v251
	v_add_co_u32_e32 v170, vcc, s17, v170
	s_waitcnt lgkmcnt(0)
	v_mul_f32_e32 v166, v211, v166
	v_cvt_pk_bf16_f32 v166, v166, s0
	v_addc_co_u32_e32 v171, vcc, 0, v171, vcc
	global_store_short v[170:171], v166, off
	v_mul_f32_e32 v166, v230, v251
	v_mul_f32_e32 v166, v166, v167
	v_cvt_pk_bf16_f32 v166, v166, s0
	global_store_short v[170:171], v166, off offset:32
	v_mul_f32_e32 v166, v187, v251
	v_mul_f32_e32 v166, v166, v168
	v_cvt_pk_bf16_f32 v166, v166, s0
	global_store_short v[170:171], v166, off offset:64
	v_mul_f32_e32 v166, v235, v251
	v_mul_f32_e32 v166, v166, v169
	v_cvt_pk_bf16_f32 v166, v166, s0
	global_store_short v[170:171], v166, off offset:96
	ds_read_b128 v[166:169], v193 offset:144
	v_mul_f32_e32 v187, v233, v251
	s_waitcnt lgkmcnt(0)
	v_mul_f32_e32 v166, v187, v166
	v_cvt_pk_bf16_f32 v166, v166, s0
	global_store_short v[170:171], v166, off offset:128
	v_mul_f32_e32 v166, v232, v251
	v_mul_f32_e32 v166, v166, v167
	v_cvt_pk_bf16_f32 v166, v166, s0
	global_store_short v[170:171], v166, off offset:160
	v_mul_f32_e32 v166, v250, v251
	v_mul_f32_e32 v166, v166, v168
	v_cvt_pk_bf16_f32 v166, v166, s0
	global_store_short v[170:171], v166, off offset:192
	v_mul_f32_e32 v166, v249, v251
	v_mul_f32_e32 v166, v166, v169
	v_cvt_pk_bf16_f32 v166, v166, s0
	global_store_short v[170:171], v166, off offset:224

.LBB0_134:
	s_waitcnt lgkmcnt(0)
	v_add_f32_e32 v166, v166, v167
	v_fmamk_f32 v166, v166, 0x3c800000, v231
	v_rsq_f32_e32 v166, v166
	s_movk_i32 s17, 0x2000
	v_cmp_gt_i32_e32 vcc, s17, v210
	s_and_b64 s[80:81], s[10:11], vcc
	v_mul_f32_e32 v167, 0x3e38aa3b, v166
	v_cndmask_b32_e64 v216, v167, v166, s[10:11]
	v_ashrrev_i32_e32 v166, 8, v210
	v_ashrrev_i32_e32 v167, 31, v166
	v_lshlrev_b64 v[166:167], 20, v[166:167]
	v_readlane_b32 vcc_lo, v254, 27
	v_lshl_add_u64 v[166:167], s[52:53], 0, v[166:167]
	v_readlane_b32 vcc_hi, v254, 28
	s_lshl_b64 s[88:89], s[66:67], 16
	v_lshlrev_b32_e32 v168, 8, v210
	v_lshl_add_u64 v[166:167], v[166:167], 0, vcc
	v_lshl_add_u64 v[166:167], v[166:167], 0, s[88:89]
	v_and_b32_e32 v168, 0xff00, v168
	v_mov_b32_e32 v169, v1
	v_lshl_add_u64 v[214:215], v[166:167], 0, v[168:169]
	ds_read_b128 v[170:173], v192 offset:16
	ds_read_b128 v[166:169], v192
	v_pk_mul_f32 v[218:219], v[146:147], v[216:217] op_sel_hi:[1,0]
	v_pk_mul_f32 v[220:221], v[148:149], v[216:217] op_sel_hi:[1,0]
	s_waitcnt lgkmcnt(0)
	v_pk_mul_f32 v[166:167], v[218:219], v[166:167]
	v_pk_mul_f32 v[168:169], v[220:221], v[168:169]
	v_pk_mul_f32 v[218:219], v[154:155], v[216:217] op_sel_hi:[1,0]
	v_pk_mul_f32 v[220:221], v[156:157], v[216:217] op_sel_hi:[1,0]
	v_pk_mul_f32 v[170:171], v[218:219], v[170:171]
	v_pk_mul_f32 v[172:173], v[220:221], v[172:173]
	v_cvt_pk_bf16_f32 v218, v166, v167
	v_cvt_pk_bf16_f32 v219, v168, v169
	v_cvt_pk_bf16_f32 v220, v170, v171
	v_cvt_pk_bf16_f32 v221, v172, v173
	global_store_dwordx4 v[212:213], v[218:221], off
	s_and_saveexec_b64 s[88:89], s[80:81]
	s_cbranch_execz .LBB0_136
	v_lshl_add_u64 v[218:219], v[214:215], 0, v[0:1]
	global_store_dwordx4 v[218:219], v[166:169], off nt
	global_store_dwordx4 v[218:219], v[170:173], off offset:16 nt
.LBB0_136:
	s_or_b64 exec, exec, s[88:89]
	s_nop 0
	ds_read_b128 v[166:169], v192 offset:128
	s_nop 0
	ds_read_b128 v[170:173], v192 offset:144
	v_mov_b32_e32 v217, v216
	v_mov_b32_e32 v218, v216
	v_mov_b32_e32 v219, v216
	s_and_b64 s[88:89], s[10:11], exec
	v_pk_mul_f32 v[220:221], v[160:161], v[218:219]
	v_pk_mul_f32 v[222:223], v[158:159], v[216:217]
	v_pk_mul_f32 v[218:219], v[164:165], v[218:219]
	v_pk_mul_f32 v[216:217], v[162:163], v[216:217]
	s_mov_b32 s89, s71
	s_cselect_b32 s88, 0x800, 64
	v_lshl_add_u64 v[212:213], v[212:213], 0, s[88:89]
	s_waitcnt lgkmcnt(1)
	v_pk_mul_f32 v[168:169], v[220:221], v[168:169]
	v_pk_mul_f32 v[166:167], v[222:223], v[166:167]
	s_waitcnt lgkmcnt(0)
	v_pk_mul_f32 v[172:173], v[218:219], v[172:173]
	v_pk_mul_f32 v[170:171], v[216:217], v[170:171]
	v_cvt_pk_bf16_f32 v216, v166, v167
	v_cvt_pk_bf16_f32 v217, v168, v169
	v_cvt_pk_bf16_f32 v218, v170, v171
	v_cvt_pk_bf16_f32 v219, v172, v173
	global_store_dwordx4 v[212:213], v[216:219], off
	s_and_saveexec_b64 s[88:89], s[80:81]
	s_cbranch_execz .LBB0_138
	v_lshl_add_u64 v[212:213], v[214:215], 0, v[0:1]
	global_store_dwordx4 v[212:213], v[166:169], off offset:128 nt
	global_store_dwordx4 v[212:213], v[170:173], off offset:144 nt

.LBB0_141:
	v_or_b32_e32 v210, 32, v204
	s_and_b64 vcc, exec, s[14:15]
	ds_read_b32 v162, v243 offset:128
	s_waitcnt lgkmcnt(0)
	s_nop 0
	v_pk_fma_f32 v[152:153], v[128:129], v[162:163], v[144:145] op_sel_hi:[1,0,1]
	v_pk_fma_f32 v[150:151], v[126:127], v[162:163], v[142:143] op_sel_hi:[1,0,1]
	v_pk_fma_f32 v[156:157], v[124:125], v[162:163], v[140:141] op_sel_hi:[1,0,1]
	v_pk_fma_f32 v[154:155], v[122:123], v[162:163], v[138:139] op_sel_hi:[1,0,1]
	v_pk_fma_f32 v[160:161], v[120:121], v[162:163], v[136:137] op_sel_hi:[1,0,1]
	v_pk_fma_f32 v[158:159], v[118:119], v[162:163], v[134:135] op_sel_hi:[1,0,1]
	v_pk_fma_f32 v[164:165], v[116:117], v[162:163], v[132:133] op_sel_hi:[1,0,1]
	v_pk_fma_f32 v[162:163], v[114:115], v[162:163], v[130:131] op_sel_hi:[1,0,1]
	s_cbranch_vccnz .LBB0_327
	s_and_b64 vcc, exec, s[12:13]
	s_mov_b64 s[80:81], -1
	s_cbranch_vccnz .LBB0_160
	v_readlane_b32 s80, v254, 60
	v_readlane_b32 s81, v254, 61
	s_andn2_b64 vcc, exec, s[80:81]
	s_mov_b64 s[80:81], -1
	s_cbranch_vccnz .LBB0_149
	v_readlane_b32 s88, v254, 62
	v_readlane_b32 s89, v254, 63
	s_andn2_b64 vcc, exec, s[88:89]
	v_mul_f32_e32 v222, 0x3d372713, v150
	v_mul_f32_e32 v220, 0x3d372713, v151
	v_mul_f32_e32 v218, 0x3d372713, v152
	v_mul_f32_e32 v216, 0x3d372713, v153
	v_mul_f32_e32 v221, 0x3d372713, v154
	v_mul_f32_e32 v219, 0x3d372713, v155
	v_mul_f32_e32 v217, 0x3d372713, v156
	v_mul_f32_e32 v215, 0x3d372713, v157
	v_mul_f32_e32 v214, 0x3d372713, v158
	v_mul_f32_e32 v212, 0x3d372713, v159
	v_mul_f32_e32 v199, 0x3d372713, v160
	v_mul_f32_e32 v173, 0x3d372713, v161
	v_mul_f32_e32 v213, 0x3d372713, v162
	v_mul_f32_e32 v205, 0x3d372713, v163
	v_mul_f32_e32 v191, 0x3d372713, v164
	v_mul_f32_e32 v172, 0x3d372713, v165
	s_cbranch_vccnz .LBB0_146
	v_mul_f32_e32 v167, v152, v218
	v_fma_f32 v167, v152, v167, v152
	v_mul_f32_e32 v167, 0x3f4c422a, v167
	v_add_f32_e32 v167, v167, v167
	v_mul_f32_e32 v167, 0xbfb8aa3b, v167
	v_exp_f32_e32 v167, v167
	v_mul_f32_e32 v166, v150, v222
	v_fma_f32 v166, v150, v166, v150
	v_mul_f32_e32 v166, 0x3f4c422a, v166
	v_add_f32_e32 v167, 1.0, v167
	v_rcp_f32_e32 v167, v167
	v_add_f32_e32 v166, v166, v166
	v_mul_f32_e32 v166, 0xbfb8aa3b, v166
	v_exp_f32_e32 v166, v166
	v_mul_f32_e32 v224, v152, v167
	v_mul_f32_e32 v167, v153, v216
	v_fma_f32 v167, v153, v167, v153
	v_mul_f32_e32 v167, 0x3f4c422a, v167
	v_add_f32_e32 v167, v167, v167
	v_mul_f32_e32 v167, 0xbfb8aa3b, v167
	v_exp_f32_e32 v167, v167
	v_add_f32_e32 v166, 1.0, v166
	v_rcp_f32_e32 v166, v166
	v_readlane_b32 s80, v255, 0
	v_add_f32_e32 v167, 1.0, v167
	v_rcp_f32_e32 v167, v167
	v_mul_f32_e32 v211, v150, v166
	v_mul_f32_e32 v166, v151, v220
	v_fma_f32 v166, v151, v166, v151
	v_mul_f32_e32 v225, v153, v167
	v_mul_f32_e32 v167, v154, v221
	v_fma_f32 v167, v154, v167, v154
	v_mul_f32_e32 v167, 0x3f4c422a, v167
	v_add_f32_e32 v167, v167, v167
	v_mul_f32_e32 v167, 0xbfb8aa3b, v167
	v_exp_f32_e32 v167, v167
	v_mul_f32_e32 v166, 0x3f4c422a, v166
	v_add_f32_e32 v166, v166, v166
	v_mul_f32_e32 v166, 0xbfb8aa3b, v166
	v_add_f32_e32 v167, 1.0, v167
	v_rcp_f32_e32 v167, v167
	v_exp_f32_e32 v166, v166
	v_readlane_b32 s81, v255, 1
	v_lshlrev_b32_e32 v168, 6, v210
	v_mul_f32_e32 v226, v154, v167
	v_mul_f32_e32 v167, v155, v219
	v_fma_f32 v167, v155, v167, v155
	v_mul_f32_e32 v167, 0x3f4c422a, v167
	v_add_f32_e32 v167, v167, v167
	v_mul_f32_e32 v167, 0xbfb8aa3b, v167
	v_exp_f32_e32 v167, v167
	v_add_f32_e32 v166, 1.0, v166
	v_rcp_f32_e32 v166, v166
	v_and_b32_e32 v168, 0x1c00, v168
	v_add_f32_e32 v167, 1.0, v167
	v_rcp_f32_e32 v167, v167
	v_mul_f32_e32 v223, v151, v166
	v_mul_f32_e32 v166, v223, v223
	v_fmac_f32_e32 v166, v211, v211
	v_mul_f32_e32 v227, v155, v167
	v_mul_f32_e32 v167, v156, v217
	v_fma_f32 v167, v156, v167, v156
	v_mul_f32_e32 v167, 0x3f4c422a, v167
	v_add_f32_e32 v167, v167, v167
	v_mul_f32_e32 v167, 0xbfb8aa3b, v167
	v_exp_f32_e32 v167, v167
	v_fmac_f32_e32 v166, v224, v224
	v_fmac_f32_e32 v166, v225, v225
	v_fmac_f32_e32 v166, v226, v226
	v_add_f32_e32 v167, 1.0, v167
	v_rcp_f32_e32 v167, v167
	v_fmac_f32_e32 v166, v227, v227
	v_mov_b32_e32 v169, v1
	v_readlane_b32 s17, v254, 15
	v_mul_f32_e32 v228, v156, v167
	v_mul_f32_e32 v167, v157, v215
	v_fma_f32 v167, v157, v167, v157
	v_mul_f32_e32 v167, 0x3f4c422a, v167
	v_add_f32_e32 v167, v167, v167
	v_mul_f32_e32 v167, 0xbfb8aa3b, v167
	v_exp_f32_e32 v167, v167
	v_fmac_f32_e32 v166, v228, v228
	v_add_f32_e32 v167, 1.0, v167
	v_rcp_f32_e32 v167, v167
	s_nop 0
	v_mul_f32_e32 v229, v157, v167
	v_mul_f32_e32 v167, v158, v214
	v_fma_f32 v167, v158, v167, v158
	v_mul_f32_e32 v167, 0x3f4c422a, v167
	v_add_f32_e32 v167, v167, v167
	v_mul_f32_e32 v167, 0xbfb8aa3b, v167
	v_exp_f32_e32 v167, v167
	v_fmac_f32_e32 v166, v229, v229
	v_add_f32_e32 v167, 1.0, v167
	v_rcp_f32_e32 v167, v167
	s_nop 0
	v_mul_f32_e32 v248, v158, v167
	v_mul_f32_e32 v167, v159, v212
	v_fma_f32 v167, v159, v167, v159
	v_mul_f32_e32 v167, 0x3f4c422a, v167
	v_add_f32_e32 v167, v167, v167
	v_mul_f32_e32 v167, 0xbfb8aa3b, v167
	v_exp_f32_e32 v167, v167
	v_fmac_f32_e32 v166, v248, v248
	v_add_f32_e32 v167, 1.0, v167
	v_rcp_f32_e32 v167, v167
	s_nop 0
	v_mul_f32_e32 v230, v159, v167
	v_mul_f32_e32 v167, v160, v199
	v_fma_f32 v167, v160, v167, v160
	v_mul_f32_e32 v167, 0x3f4c422a, v167
	v_add_f32_e32 v167, v167, v167
	v_mul_f32_e32 v167, 0xbfb8aa3b, v167
	v_exp_f32_e32 v167, v167
	v_fmac_f32_e32 v166, v230, v230
	v_add_f32_e32 v167, 1.0, v167
	v_rcp_f32_e32 v167, v167
	s_nop 0
	v_mul_f32_e32 v187, v160, v167
	v_mul_f32_e32 v167, v161, v173
	v_fma_f32 v167, v161, v167, v161
	v_mul_f32_e32 v167, 0x3f4c422a, v167
	v_add_f32_e32 v167, v167, v167
	v_mul_f32_e32 v167, 0xbfb8aa3b, v167
	v_exp_f32_e32 v167, v167
	v_fmac_f32_e32 v166, v187, v187
	v_add_f32_e32 v167, 1.0, v167
	v_rcp_f32_e32 v167, v167
	s_nop 0
	v_mul_f32_e32 v235, v161, v167
	v_mul_f32_e32 v167, v162, v213
	v_fma_f32 v167, v162, v167, v162
	v_mul_f32_e32 v167, 0x3f4c422a, v167
	v_add_f32_e32 v167, v167, v167
	v_mul_f32_e32 v167, 0xbfb8aa3b, v167
	v_exp_f32_e32 v167, v167
	v_fmac_f32_e32 v166, v235, v235
	v_add_f32_e32 v167, 1.0, v167
	v_rcp_f32_e32 v167, v167
	s_nop 0
	v_mul_f32_e32 v233, v162, v167
	v_mul_f32_e32 v167, v163, v205
	v_fma_f32 v167, v163, v167, v163
	v_mul_f32_e32 v167, 0x3f4c422a, v167
	v_add_f32_e32 v167, v167, v167
	v_mul_f32_e32 v167, 0xbfb8aa3b, v167
	v_exp_f32_e32 v167, v167
	v_fmac_f32_e32 v166, v233, v233
	v_add_f32_e32 v167, 1.0, v167
	v_rcp_f32_e32 v167, v167
	s_nop 0
	v_mul_f32_e32 v232, v163, v167
	v_mul_f32_e32 v167, v164, v191
	v_fma_f32 v167, v164, v167, v164
	v_mul_f32_e32 v167, 0x3f4c422a, v167
	v_add_f32_e32 v167, v167, v167
	v_mul_f32_e32 v167, 0xbfb8aa3b, v167
	v_exp_f32_e32 v167, v167
	v_fmac_f32_e32 v166, v232, v232
	v_add_f32_e32 v167, 1.0, v167
	v_rcp_f32_e32 v167, v167
	s_nop 0
	v_mul_f32_e32 v250, v164, v167
	v_mul_f32_e32 v167, v165, v172
	v_fma_f32 v167, v165, v167, v165
	v_mul_f32_e32 v167, 0x3f4c422a, v167
	v_add_f32_e32 v167, v167, v167
	v_mul_f32_e32 v167, 0xbfb8aa3b, v167
	v_exp_f32_e32 v167, v167
	v_fmac_f32_e32 v166, v250, v250
	v_add_f32_e32 v167, 1.0, v167
	v_rcp_f32_e32 v167, v167
	s_nop 0
	v_mul_f32_e32 v249, v165, v167
	v_fmac_f32_e32 v166, v249, v249
	ds_bpermute_b32 v167, v244, v166
	s_waitcnt lgkmcnt(0)
	v_add_f32_e32 v166, v166, v167
	ds_bpermute_b32 v167, v245, v166
	s_waitcnt lgkmcnt(0)
	v_add_f32_e32 v166, v166, v167
	v_fmamk_f32 v166, v166, 0x3c800000, v231
	v_rsq_f32_e32 v251, v166
	v_ashrrev_i32_e32 v166, 7, v210
	v_ashrrev_i32_e32 v167, 31, v166
	v_lshlrev_b64 v[166:167], 16, v[166:167]
	v_lshl_add_u64 v[166:167], s[80:81], 0, v[166:167]
	v_lshl_add_u64 v[166:167], v[166:167], 0, v[168:169]
	v_and_b32_e32 v168, 8, v210
	v_lshlrev_b32_e32 v168, 1, v168
	v_lshl_add_u64 v[166:167], v[166:167], 0, v[168:169]
	v_and_b32_e32 v168, 7, v210
	v_lshlrev_b32_e32 v168, 1, v168
	v_lshl_add_u64 v[166:167], v[166:167], 0, v[168:169]
	s_lshl_b32 s80, s17, 1
	s_mov_b32 s81, s71
	v_lshl_add_u64 v[166:167], v[166:167], 0, s[80:81]
	v_lshlrev_b32_e32 v168, 1, v186
	v_lshl_add_u64 v[170:171], v[166:167], 0, v[168:169]
	ds_read_b128 v[166:169], v193
	v_mul_f32_e32 v211, v211, v251
	s_movk_i32 s17, 0x2000
	s_mov_b64 s[80:81], 0
	s_waitcnt lgkmcnt(0)
	v_mul_f32_e32 v166, v166, v211
	v_cvt_pk_bf16_f32 v166, v166, s0
	global_store_short v[170:171], v166, off
	v_mul_f32_e32 v166, v223, v251
	v_mul_f32_e32 v166, v167, v166
	v_cvt_pk_bf16_f32 v166, v166, s0
	global_store_short v[170:171], v166, off offset:32
	v_mul_f32_e32 v166, v224, v251
	v_mul_f32_e32 v166, v168, v166
	v_cvt_pk_bf16_f32 v166, v166, s0
	global_store_short v[170:171], v166, off offset:64
	v_mul_f32_e32 v166, v225, v251
	v_mul_f32_e32 v166, v169, v166
	v_cvt_pk_bf16_f32 v166, v166, s0
	global_store_short v[170:171], v166, off offset:96
	ds_read_b128 v[166:169], v193 offset:16
	v_mul_f32_e32 v211, v226, v251
	s_waitcnt lgkmcnt(0)
	v_mul_f32_e32 v166, v211, v166
	v_cvt_pk_bf16_f32 v166, v166, s0
	global_store_short v[170:171], v166, off offset:128
	v_mul_f32_e32 v166, v227, v251
	v_mul_f32_e32 v166, v166, v167
	v_cvt_pk_bf16_f32 v166, v166, s0
	global_store_short v[170:171], v166, off offset:160
	v_mul_f32_e32 v166, v228, v251
	v_mul_f32_e32 v166, v166, v168
	v_cvt_pk_bf16_f32 v166, v166, s0
	global_store_short v[170:171], v166, off offset:192
	v_mul_f32_e32 v166, v229, v251
	v_mul_f32_e32 v166, v166, v169
	v_cvt_pk_bf16_f32 v166, v166, s0
	global_store_short v[170:171], v166, off offset:224
	ds_read_b128 v[166:169], v193 offset:128
	v_mul_f32_e32 v211, v248, v251
	v_add_co_u32_e32 v170, vcc, s17, v170
	s_waitcnt lgkmcnt(0)
	v_mul_f32_e32 v166, v211, v166
	v_cvt_pk_bf16_f32 v166, v166, s0
	v_addc_co_u32_e32 v171, vcc, 0, v171, vcc
	global_store_short v[170:171], v166, off
	v_mul_f32_e32 v166, v230, v251
	v_mul_f32_e32 v166, v166, v167
	v_cvt_pk_bf16_f32 v166, v166, s0
	global_store_short v[170:171], v166, off offset:32
	v_mul_f32_e32 v166, v187, v251
	v_mul_f32_e32 v166, v166, v168
	v_cvt_pk_bf16_f32 v166, v166, s0
	global_store_short v[170:171], v166, off offset:64
	v_mul_f32_e32 v166, v235, v251
	v_mul_f32_e32 v166, v166, v169
	v_cvt_pk_bf16_f32 v166, v166, s0
	global_store_short v[170:171], v166, off offset:96
	ds_read_b128 v[166:169], v193 offset:144
	v_mul_f32_e32 v187, v233, v251
	s_waitcnt lgkmcnt(0)
	v_mul_f32_e32 v166, v187, v166
	v_cvt_pk_bf16_f32 v166, v166, s0
	global_store_short v[170:171], v166, off offset:128
	v_mul_f32_e32 v166, v232, v251
	v_mul_f32_e32 v166, v166, v167
	v_cvt_pk_bf16_f32 v166, v166, s0
	global_store_short v[170:171], v166, off offset:160
	v_mul_f32_e32 v166, v250, v251
	v_mul_f32_e32 v166, v166, v168
	v_cvt_pk_bf16_f32 v166, v166, s0
	global_store_short v[170:171], v166, off offset:192
	v_mul_f32_e32 v166, v249, v251
	v_mul_f32_e32 v166, v166, v169
	v_cvt_pk_bf16_f32 v166, v166, s0
	global_store_short v[170:171], v166, off offset:224

.LBB0_165:
	s_waitcnt lgkmcnt(0)
	v_add_f32_e32 v166, v166, v167
	v_fmamk_f32 v166, v166, 0x3c800000, v231
	v_rsq_f32_e32 v166, v166
	s_movk_i32 s17, 0x2000
	v_cmp_gt_i32_e32 vcc, s17, v210
	s_and_b64 s[80:81], s[10:11], vcc
	v_mul_f32_e32 v167, 0x3e38aa3b, v166
	v_cndmask_b32_e64 v216, v167, v166, s[10:11]
	v_ashrrev_i32_e32 v166, 8, v210
	v_ashrrev_i32_e32 v167, 31, v166
	v_lshlrev_b64 v[166:167], 20, v[166:167]
	v_readlane_b32 vcc_lo, v254, 27
	v_lshl_add_u64 v[166:167], s[52:53], 0, v[166:167]
	v_readlane_b32 vcc_hi, v254, 28
	s_lshl_b64 s[88:89], s[66:67], 16
	v_lshlrev_b32_e32 v168, 8, v210
	v_lshl_add_u64 v[166:167], v[166:167], 0, vcc
	v_lshl_add_u64 v[166:167], v[166:167], 0, s[88:89]
	v_and_b32_e32 v168, 0xff00, v168
	v_mov_b32_e32 v169, v1
	v_lshl_add_u64 v[214:215], v[166:167], 0, v[168:169]
	ds_read_b128 v[170:173], v192 offset:16
	ds_read_b128 v[166:169], v192
	v_pk_mul_f32 v[218:219], v[150:151], v[216:217] op_sel_hi:[1,0]
	v_pk_mul_f32 v[220:221], v[152:153], v[216:217] op_sel_hi:[1,0]
	s_waitcnt lgkmcnt(0)
	v_pk_mul_f32 v[166:167], v[218:219], v[166:167]
	v_pk_mul_f32 v[168:169], v[220:221], v[168:169]
	v_pk_mul_f32 v[218:219], v[154:155], v[216:217] op_sel_hi:[1,0]
	v_pk_mul_f32 v[220:221], v[156:157], v[216:217] op_sel_hi:[1,0]
	v_pk_mul_f32 v[170:171], v[218:219], v[170:171]
	v_pk_mul_f32 v[172:173], v[220:221], v[172:173]
	v_cvt_pk_bf16_f32 v218, v166, v167
	v_cvt_pk_bf16_f32 v219, v168, v169
	v_cvt_pk_bf16_f32 v220, v170, v171
	v_cvt_pk_bf16_f32 v221, v172, v173
	global_store_dwordx4 v[212:213], v[218:221], off
	s_and_saveexec_b64 s[88:89], s[80:81]
	s_cbranch_execz .LBB0_167
	v_lshl_add_u64 v[218:219], v[214:215], 0, v[0:1]
	global_store_dwordx4 v[218:219], v[166:169], off nt
	global_store_dwordx4 v[218:219], v[170:173], off offset:16 nt

.LBB0_172:
	v_or_b32_e32 v210, 48, v204
	s_and_b64 vcc, exec, s[14:15]
	ds_read_b32 v162, v243 offset:192
	s_waitcnt lgkmcnt(0)
	s_nop 0
	v_pk_fma_f32 v[148:149], v[112:113], v[162:163], v[144:145] op_sel_hi:[1,0,1]
	v_pk_fma_f32 v[146:147], v[110:111], v[162:163], v[142:143] op_sel_hi:[1,0,1]
	v_pk_fma_f32 v[156:157], v[108:109], v[162:163], v[140:141] op_sel_hi:[1,0,1]
	v_pk_fma_f32 v[154:155], v[106:107], v[162:163], v[138:139] op_sel_hi:[1,0,1]
	v_pk_fma_f32 v[160:161], v[104:105], v[162:163], v[136:137] op_sel_hi:[1,0,1]
	v_pk_fma_f32 v[158:159], v[102:103], v[162:163], v[134:135] op_sel_hi:[1,0,1]
	v_pk_fma_f32 v[164:165], v[100:101], v[162:163], v[132:133] op_sel_hi:[1,0,1]
	v_pk_fma_f32 v[162:163], v[98:99], v[162:163], v[130:131] op_sel_hi:[1,0,1]
	s_cbranch_vccnz .LBB0_328
	s_and_b64 vcc, exec, s[12:13]
	s_mov_b64 s[80:81], -1
	s_cbranch_vccnz .LBB0_191
	v_readlane_b32 s80, v254, 60
	v_readlane_b32 s81, v254, 61
	s_andn2_b64 vcc, exec, s[80:81]
	s_mov_b64 s[80:81], -1
	s_cbranch_vccnz .LBB0_180
	v_readlane_b32 s88, v254, 62
	v_readlane_b32 s89, v254, 63
	s_andn2_b64 vcc, exec, s[88:89]
	v_mul_f32_e32 v222, 0x3d372713, v146
	v_mul_f32_e32 v220, 0x3d372713, v147
	v_mul_f32_e32 v218, 0x3d372713, v148
	v_mul_f32_e32 v216, 0x3d372713, v149
	v_mul_f32_e32 v221, 0x3d372713, v154
	v_mul_f32_e32 v219, 0x3d372713, v155
	v_mul_f32_e32 v217, 0x3d372713, v156
	v_mul_f32_e32 v215, 0x3d372713, v157
	v_mul_f32_e32 v214, 0x3d372713, v158
	v_mul_f32_e32 v212, 0x3d372713, v159
	v_mul_f32_e32 v199, 0x3d372713, v160
	v_mul_f32_e32 v173, 0x3d372713, v161
	v_mul_f32_e32 v213, 0x3d372713, v162
	v_mul_f32_e32 v205, 0x3d372713, v163
	v_mul_f32_e32 v191, 0x3d372713, v164
	v_mul_f32_e32 v172, 0x3d372713, v165
	s_cbranch_vccnz .LBB0_177
	v_mul_f32_e32 v167, v148, v218
	v_fma_f32 v167, v148, v167, v148
	v_mul_f32_e32 v167, 0x3f4c422a, v167
	v_add_f32_e32 v167, v167, v167
	v_mul_f32_e32 v167, 0xbfb8aa3b, v167
	v_exp_f32_e32 v167, v167
	v_mul_f32_e32 v166, v146, v222
	v_fma_f32 v166, v146, v166, v146
	v_mul_f32_e32 v166, 0x3f4c422a, v166
	v_add_f32_e32 v167, 1.0, v167
	v_rcp_f32_e32 v167, v167
	v_add_f32_e32 v166, v166, v166
	v_mul_f32_e32 v166, 0xbfb8aa3b, v166
	v_exp_f32_e32 v166, v166
	v_mul_f32_e32 v224, v148, v167
	v_mul_f32_e32 v167, v149, v216
	v_fma_f32 v167, v149, v167, v149
	v_mul_f32_e32 v167, 0x3f4c422a, v167
	v_add_f32_e32 v167, v167, v167
	v_mul_f32_e32 v167, 0xbfb8aa3b, v167
	v_exp_f32_e32 v167, v167
	v_add_f32_e32 v166, 1.0, v166
	v_rcp_f32_e32 v166, v166
	v_readlane_b32 s80, v255, 0
	v_add_f32_e32 v167, 1.0, v167
	v_rcp_f32_e32 v167, v167
	v_mul_f32_e32 v211, v146, v166
	v_mul_f32_e32 v166, v147, v220
	v_fma_f32 v166, v147, v166, v147
	v_mul_f32_e32 v225, v149, v167
	v_mul_f32_e32 v167, v154, v221
	v_fma_f32 v167, v154, v167, v154
	v_mul_f32_e32 v167, 0x3f4c422a, v167
	v_add_f32_e32 v167, v167, v167
	v_mul_f32_e32 v167, 0xbfb8aa3b, v167
	v_exp_f32_e32 v167, v167
	v_mul_f32_e32 v166, 0x3f4c422a, v166
	v_add_f32_e32 v166, v166, v166
	v_mul_f32_e32 v166, 0xbfb8aa3b, v166
	v_add_f32_e32 v167, 1.0, v167
	v_rcp_f32_e32 v167, v167
	v_exp_f32_e32 v166, v166
	v_readlane_b32 s81, v255, 1
	v_lshlrev_b32_e32 v168, 6, v210
	v_mul_f32_e32 v226, v154, v167
	v_mul_f32_e32 v167, v155, v219
	v_fma_f32 v167, v155, v167, v155
	v_mul_f32_e32 v167, 0x3f4c422a, v167
	v_add_f32_e32 v167, v167, v167
	v_mul_f32_e32 v167, 0xbfb8aa3b, v167
	v_exp_f32_e32 v167, v167
	v_add_f32_e32 v166, 1.0, v166
	v_rcp_f32_e32 v166, v166
	v_and_b32_e32 v168, 0x1c00, v168
	v_add_f32_e32 v167, 1.0, v167
	v_rcp_f32_e32 v167, v167
	v_mul_f32_e32 v223, v147, v166
	v_mul_f32_e32 v166, v223, v223
	v_fmac_f32_e32 v166, v211, v211
	v_mul_f32_e32 v227, v155, v167
	v_mul_f32_e32 v167, v156, v217
	v_fma_f32 v167, v156, v167, v156
	v_mul_f32_e32 v167, 0x3f4c422a, v167
	v_add_f32_e32 v167, v167, v167
	v_mul_f32_e32 v167, 0xbfb8aa3b, v167
	v_exp_f32_e32 v167, v167
	v_fmac_f32_e32 v166, v224, v224
	v_fmac_f32_e32 v166, v225, v225
	v_fmac_f32_e32 v166, v226, v226
	v_add_f32_e32 v167, 1.0, v167
	v_rcp_f32_e32 v167, v167
	v_fmac_f32_e32 v166, v227, v227
	v_mov_b32_e32 v169, v1
	v_readlane_b32 s17, v254, 15
	v_mul_f32_e32 v228, v156, v167
	v_mul_f32_e32 v167, v157, v215
	v_fma_f32 v167, v157, v167, v157
	v_mul_f32_e32 v167, 0x3f4c422a, v167
	v_add_f32_e32 v167, v167, v167
	v_mul_f32_e32 v167, 0xbfb8aa3b, v167
	v_exp_f32_e32 v167, v167
	v_fmac_f32_e32 v166, v228, v228
	v_add_f32_e32 v167, 1.0, v167
	v_rcp_f32_e32 v167, v167
	s_nop 0
	v_mul_f32_e32 v229, v157, v167
	v_mul_f32_e32 v167, v158, v214
	v_fma_f32 v167, v158, v167, v158
	v_mul_f32_e32 v167, 0x3f4c422a, v167
	v_add_f32_e32 v167, v167, v167
	v_mul_f32_e32 v167, 0xbfb8aa3b, v167
	v_exp_f32_e32 v167, v167
	v_fmac_f32_e32 v166, v229, v229
	v_add_f32_e32 v167, 1.0, v167
	v_rcp_f32_e32 v167, v167
	s_nop 0
	v_mul_f32_e32 v248, v158, v167
	v_mul_f32_e32 v167, v159, v212
	v_fma_f32 v167, v159, v167, v159
	v_mul_f32_e32 v167, 0x3f4c422a, v167
	v_add_f32_e32 v167, v167, v167
	v_mul_f32_e32 v167, 0xbfb8aa3b, v167
	v_exp_f32_e32 v167, v167
	v_fmac_f32_e32 v166, v248, v248
	v_add_f32_e32 v167, 1.0, v167
	v_rcp_f32_e32 v167, v167
	s_nop 0
	v_mul_f32_e32 v230, v159, v167
	v_mul_f32_e32 v167, v160, v199
	v_fma_f32 v167, v160, v167, v160
	v_mul_f32_e32 v167, 0x3f4c422a, v167
	v_add_f32_e32 v167, v167, v167
	v_mul_f32_e32 v167, 0xbfb8aa3b, v167
	v_exp_f32_e32 v167, v167
	v_fmac_f32_e32 v166, v230, v230
	v_add_f32_e32 v167, 1.0, v167
	v_rcp_f32_e32 v167, v167
	s_nop 0
	v_mul_f32_e32 v187, v160, v167
	v_mul_f32_e32 v167, v161, v173
	v_fma_f32 v167, v161, v167, v161
	v_mul_f32_e32 v167, 0x3f4c422a, v167
	v_add_f32_e32 v167, v167, v167
	v_mul_f32_e32 v167, 0xbfb8aa3b, v167
	v_exp_f32_e32 v167, v167
	v_fmac_f32_e32 v166, v187, v187
	v_add_f32_e32 v167, 1.0, v167
	v_rcp_f32_e32 v167, v167
	s_nop 0
	v_mul_f32_e32 v235, v161, v167
	v_mul_f32_e32 v167, v162, v213
	v_fma_f32 v167, v162, v167, v162
	v_mul_f32_e32 v167, 0x3f4c422a, v167
	v_add_f32_e32 v167, v167, v167
	v_mul_f32_e32 v167, 0xbfb8aa3b, v167
	v_exp_f32_e32 v167, v167
	v_fmac_f32_e32 v166, v235, v235
	v_add_f32_e32 v167, 1.0, v167
	v_rcp_f32_e32 v167, v167
	s_nop 0
	v_mul_f32_e32 v233, v162, v167
	v_mul_f32_e32 v167, v163, v205
	v_fma_f32 v167, v163, v167, v163
	v_mul_f32_e32 v167, 0x3f4c422a, v167
	v_add_f32_e32 v167, v167, v167
	v_mul_f32_e32 v167, 0xbfb8aa3b, v167
	v_exp_f32_e32 v167, v167
	v_fmac_f32_e32 v166, v233, v233
	v_add_f32_e32 v167, 1.0, v167
	v_rcp_f32_e32 v167, v167
	s_nop 0
	v_mul_f32_e32 v232, v163, v167
	v_mul_f32_e32 v167, v164, v191
	v_fma_f32 v167, v164, v167, v164
	v_mul_f32_e32 v167, 0x3f4c422a, v167
	v_add_f32_e32 v167, v167, v167
	v_mul_f32_e32 v167, 0xbfb8aa3b, v167
	v_exp_f32_e32 v167, v167
	v_fmac_f32_e32 v166, v232, v232
	v_add_f32_e32 v167, 1.0, v167
	v_rcp_f32_e32 v167, v167
	s_nop 0
	v_mul_f32_e32 v250, v164, v167
	v_mul_f32_e32 v167, v165, v172
	v_fma_f32 v167, v165, v167, v165
	v_mul_f32_e32 v167, 0x3f4c422a, v167
	v_add_f32_e32 v167, v167, v167
	v_mul_f32_e32 v167, 0xbfb8aa3b, v167
	v_exp_f32_e32 v167, v167
	v_fmac_f32_e32 v166, v250, v250
	v_add_f32_e32 v167, 1.0, v167
	v_rcp_f32_e32 v167, v167
	s_nop 0
	v_mul_f32_e32 v249, v165, v167
	v_fmac_f32_e32 v166, v249, v249
	ds_bpermute_b32 v167, v244, v166
	s_waitcnt lgkmcnt(0)
	v_add_f32_e32 v166, v166, v167
	ds_bpermute_b32 v167, v245, v166
	s_waitcnt lgkmcnt(0)
	v_add_f32_e32 v166, v166, v167
	v_fmamk_f32 v166, v166, 0x3c800000, v231
	v_rsq_f32_e32 v251, v166
	v_ashrrev_i32_e32 v166, 7, v210
	v_ashrrev_i32_e32 v167, 31, v166
	v_lshlrev_b64 v[166:167], 16, v[166:167]
	v_lshl_add_u64 v[166:167], s[80:81], 0, v[166:167]
	v_lshl_add_u64 v[166:167], v[166:167], 0, v[168:169]
	v_and_b32_e32 v168, 8, v210
	v_lshlrev_b32_e32 v168, 1, v168
	v_lshl_add_u64 v[166:167], v[166:167], 0, v[168:169]
	v_and_b32_e32 v168, 7, v210
	v_lshlrev_b32_e32 v168, 1, v168
	v_lshl_add_u64 v[166:167], v[166:167], 0, v[168:169]
	s_lshl_b32 s80, s17, 1
	s_mov_b32 s81, s71
	v_lshl_add_u64 v[166:167], v[166:167], 0, s[80:81]
	v_lshlrev_b32_e32 v168, 1, v186
	v_lshl_add_u64 v[170:171], v[166:167], 0, v[168:169]
	ds_read_b128 v[166:169], v193
	v_mul_f32_e32 v211, v211, v251
	s_movk_i32 s17, 0x2000
	s_mov_b64 s[80:81], 0
	s_waitcnt lgkmcnt(0)
	v_mul_f32_e32 v166, v166, v211
	v_cvt_pk_bf16_f32 v166, v166, s0
	global_store_short v[170:171], v166, off
	v_mul_f32_e32 v166, v223, v251
	v_mul_f32_e32 v166, v167, v166
	v_cvt_pk_bf16_f32 v166, v166, s0
	global_store_short v[170:171], v166, off offset:32
	v_mul_f32_e32 v166, v224, v251
	v_mul_f32_e32 v166, v168, v166
	v_cvt_pk_bf16_f32 v166, v166, s0
	global_store_short v[170:171], v166, off offset:64
	v_mul_f32_e32 v166, v225, v251
	v_mul_f32_e32 v166, v169, v166
	v_cvt_pk_bf16_f32 v166, v166, s0
	global_store_short v[170:171], v166, off offset:96
	ds_read_b128 v[166:169], v193 offset:16
	v_mul_f32_e32 v211, v226, v251
	s_waitcnt lgkmcnt(0)
	v_mul_f32_e32 v166, v211, v166
	v_cvt_pk_bf16_f32 v166, v166, s0
	global_store_short v[170:171], v166, off offset:128
	v_mul_f32_e32 v166, v227, v251
	v_mul_f32_e32 v166, v166, v167
	v_cvt_pk_bf16_f32 v166, v166, s0
	global_store_short v[170:171], v166, off offset:160
	v_mul_f32_e32 v166, v228, v251
	v_mul_f32_e32 v166, v166, v168
	v_cvt_pk_bf16_f32 v166, v166, s0
	global_store_short v[170:171], v166, off offset:192
	v_mul_f32_e32 v166, v229, v251
	v_mul_f32_e32 v166, v166, v169
	v_cvt_pk_bf16_f32 v166, v166, s0
	global_store_short v[170:171], v166, off offset:224
	ds_read_b128 v[166:169], v193 offset:128
	v_mul_f32_e32 v211, v248, v251
	v_add_co_u32_e32 v170, vcc, s17, v170
	s_waitcnt lgkmcnt(0)
	v_mul_f32_e32 v166, v211, v166
	v_cvt_pk_bf16_f32 v166, v166, s0
	v_addc_co_u32_e32 v171, vcc, 0, v171, vcc
	global_store_short v[170:171], v166, off
	v_mul_f32_e32 v166, v230, v251
	v_mul_f32_e32 v166, v166, v167
	v_cvt_pk_bf16_f32 v166, v166, s0
	global_store_short v[170:171], v166, off offset:32
	v_mul_f32_e32 v166, v187, v251
	v_mul_f32_e32 v166, v166, v168
	v_cvt_pk_bf16_f32 v166, v166, s0
	global_store_short v[170:171], v166, off offset:64
	v_mul_f32_e32 v166, v235, v251
	v_mul_f32_e32 v166, v166, v169
	v_cvt_pk_bf16_f32 v166, v166, s0
	global_store_short v[170:171], v166, off offset:96
	ds_read_b128 v[166:169], v193 offset:144
	v_mul_f32_e32 v187, v233, v251
	s_waitcnt lgkmcnt(0)
	v_mul_f32_e32 v166, v187, v166
	v_cvt_pk_bf16_f32 v166, v166, s0
	global_store_short v[170:171], v166, off offset:128
	v_mul_f32_e32 v166, v232, v251
	v_mul_f32_e32 v166, v166, v167
	v_cvt_pk_bf16_f32 v166, v166, s0
	global_store_short v[170:171], v166, off offset:160
	v_mul_f32_e32 v166, v250, v251
	v_mul_f32_e32 v166, v166, v168
	v_cvt_pk_bf16_f32 v166, v166, s0
	global_store_short v[170:171], v166, off offset:192
	v_mul_f32_e32 v166, v249, v251
	v_mul_f32_e32 v166, v166, v169
	v_cvt_pk_bf16_f32 v166, v166, s0
	global_store_short v[170:171], v166, off offset:224

.LBB0_203:
	v_add_u32_e32 v210, 0x80, v204
	s_and_b64 vcc, exec, s[14:15]
	ds_read_b32 v162, v243 offset:512
	s_waitcnt lgkmcnt(0)
	s_nop 0
	v_pk_fma_f32 v[152:153], v[96:97], v[162:163], v[144:145] op_sel_hi:[1,0,1]
	v_pk_fma_f32 v[150:151], v[94:95], v[162:163], v[142:143] op_sel_hi:[1,0,1]
	v_pk_fma_f32 v[156:157], v[92:93], v[162:163], v[140:141] op_sel_hi:[1,0,1]
	v_pk_fma_f32 v[154:155], v[90:91], v[162:163], v[138:139] op_sel_hi:[1,0,1]
	v_pk_fma_f32 v[160:161], v[88:89], v[162:163], v[136:137] op_sel_hi:[1,0,1]
	v_pk_fma_f32 v[158:159], v[86:87], v[162:163], v[134:135] op_sel_hi:[1,0,1]
	v_pk_fma_f32 v[164:165], v[84:85], v[162:163], v[132:133] op_sel_hi:[1,0,1]
	v_pk_fma_f32 v[162:163], v[82:83], v[162:163], v[130:131] op_sel_hi:[1,0,1]
	s_cbranch_vccnz .LBB0_329
	s_and_b64 vcc, exec, s[12:13]
	s_mov_b64 s[80:81], -1
	s_cbranch_vccnz .LBB0_222
	v_readlane_b32 s80, v254, 60
	v_readlane_b32 s81, v254, 61
	s_andn2_b64 vcc, exec, s[80:81]
	s_mov_b64 s[80:81], -1
	s_cbranch_vccnz .LBB0_211
	v_readlane_b32 s88, v254, 62
	v_readlane_b32 s89, v254, 63
	s_andn2_b64 vcc, exec, s[88:89]
	v_mul_f32_e32 v222, 0x3d372713, v150
	v_mul_f32_e32 v220, 0x3d372713, v151
	v_mul_f32_e32 v218, 0x3d372713, v152
	v_mul_f32_e32 v216, 0x3d372713, v153
	v_mul_f32_e32 v221, 0x3d372713, v154
	v_mul_f32_e32 v219, 0x3d372713, v155
	v_mul_f32_e32 v217, 0x3d372713, v156
	v_mul_f32_e32 v215, 0x3d372713, v157
	v_mul_f32_e32 v214, 0x3d372713, v158
	v_mul_f32_e32 v212, 0x3d372713, v159
	v_mul_f32_e32 v199, 0x3d372713, v160
	v_mul_f32_e32 v173, 0x3d372713, v161
	v_mul_f32_e32 v213, 0x3d372713, v162
	v_mul_f32_e32 v205, 0x3d372713, v163
	v_mul_f32_e32 v191, 0x3d372713, v164
	v_mul_f32_e32 v172, 0x3d372713, v165
	s_cbranch_vccnz .LBB0_208
	v_mul_f32_e32 v167, v152, v218
	v_fma_f32 v167, v152, v167, v152
	v_mul_f32_e32 v167, 0x3f4c422a, v167
	v_add_f32_e32 v167, v167, v167
	v_mul_f32_e32 v167, 0xbfb8aa3b, v167
	v_exp_f32_e32 v167, v167
	v_mul_f32_e32 v166, v150, v222
	v_fma_f32 v166, v150, v166, v150
	v_mul_f32_e32 v166, 0x3f4c422a, v166
	v_add_f32_e32 v167, 1.0, v167
	v_rcp_f32_e32 v167, v167
	v_add_f32_e32 v166, v166, v166
	v_mul_f32_e32 v166, 0xbfb8aa3b, v166
	v_exp_f32_e32 v166, v166
	v_mul_f32_e32 v224, v152, v167
	v_mul_f32_e32 v167, v153, v216
	v_fma_f32 v167, v153, v167, v153
	v_mul_f32_e32 v167, 0x3f4c422a, v167
	v_add_f32_e32 v167, v167, v167
	v_mul_f32_e32 v167, 0xbfb8aa3b, v167
	v_exp_f32_e32 v167, v167
	v_add_f32_e32 v166, 1.0, v166
	v_rcp_f32_e32 v166, v166
	v_readlane_b32 s80, v255, 0
	v_add_f32_e32 v167, 1.0, v167
	v_rcp_f32_e32 v167, v167
	v_mul_f32_e32 v211, v150, v166
	v_mul_f32_e32 v166, v151, v220
	v_fma_f32 v166, v151, v166, v151
	v_mul_f32_e32 v225, v153, v167
	v_mul_f32_e32 v167, v154, v221
	v_fma_f32 v167, v154, v167, v154
	v_mul_f32_e32 v167, 0x3f4c422a, v167
	v_add_f32_e32 v167, v167, v167
	v_mul_f32_e32 v167, 0xbfb8aa3b, v167
	v_exp_f32_e32 v167, v167
	v_mul_f32_e32 v166, 0x3f4c422a, v166
	v_add_f32_e32 v166, v166, v166
	v_mul_f32_e32 v166, 0xbfb8aa3b, v166
	v_add_f32_e32 v167, 1.0, v167
	v_rcp_f32_e32 v167, v167
	v_exp_f32_e32 v166, v166
	v_readlane_b32 s81, v255, 1
	v_lshlrev_b32_e32 v168, 6, v210
	v_mul_f32_e32 v226, v154, v167
	v_mul_f32_e32 v167, v155, v219
	v_fma_f32 v167, v155, v167, v155
	v_mul_f32_e32 v167, 0x3f4c422a, v167
	v_add_f32_e32 v167, v167, v167
	v_mul_f32_e32 v167, 0xbfb8aa3b, v167
	v_exp_f32_e32 v167, v167
	v_add_f32_e32 v166, 1.0, v166
	v_rcp_f32_e32 v166, v166
	v_and_b32_e32 v168, 0x1c00, v168
	v_add_f32_e32 v167, 1.0, v167
	v_rcp_f32_e32 v167, v167
	v_mul_f32_e32 v223, v151, v166
	v_mul_f32_e32 v166, v223, v223
	v_fmac_f32_e32 v166, v211, v211
	v_mul_f32_e32 v227, v155, v167
	v_mul_f32_e32 v167, v156, v217
	v_fma_f32 v167, v156, v167, v156
	v_mul_f32_e32 v167, 0x3f4c422a, v167
	v_add_f32_e32 v167, v167, v167
	v_mul_f32_e32 v167, 0xbfb8aa3b, v167
	v_exp_f32_e32 v167, v167
	v_fmac_f32_e32 v166, v224, v224
	v_fmac_f32_e32 v166, v225, v225
	v_fmac_f32_e32 v166, v226, v226
	v_add_f32_e32 v167, 1.0, v167
	v_rcp_f32_e32 v167, v167
	v_fmac_f32_e32 v166, v227, v227
	v_mov_b32_e32 v169, v1
	v_readlane_b32 s17, v254, 15
	v_mul_f32_e32 v228, v156, v167
	v_mul_f32_e32 v167, v157, v215
	v_fma_f32 v167, v157, v167, v157
	v_mul_f32_e32 v167, 0x3f4c422a, v167
	v_add_f32_e32 v167, v167, v167
	v_mul_f32_e32 v167, 0xbfb8aa3b, v167
	v_exp_f32_e32 v167, v167
	v_fmac_f32_e32 v166, v228, v228
	v_add_f32_e32 v167, 1.0, v167
	v_rcp_f32_e32 v167, v167
	s_nop 0
	v_mul_f32_e32 v229, v157, v167
	v_mul_f32_e32 v167, v158, v214
	v_fma_f32 v167, v158, v167, v158
	v_mul_f32_e32 v167, 0x3f4c422a, v167
	v_add_f32_e32 v167, v167, v167
	v_mul_f32_e32 v167, 0xbfb8aa3b, v167
	v_exp_f32_e32 v167, v167
	v_fmac_f32_e32 v166, v229, v229
	v_add_f32_e32 v167, 1.0, v167
	v_rcp_f32_e32 v167, v167
	s_nop 0
	v_mul_f32_e32 v248, v158, v167
	v_mul_f32_e32 v167, v159, v212
	v_fma_f32 v167, v159, v167, v159
	v_mul_f32_e32 v167, 0x3f4c422a, v167
	v_add_f32_e32 v167, v167, v167
	v_mul_f32_e32 v167, 0xbfb8aa3b, v167
	v_exp_f32_e32 v167, v167
	v_fmac_f32_e32 v166, v248, v248
	v_add_f32_e32 v167, 1.0, v167
	v_rcp_f32_e32 v167, v167
	s_nop 0
	v_mul_f32_e32 v230, v159, v167
	v_mul_f32_e32 v167, v160, v199
	v_fma_f32 v167, v160, v167, v160
	v_mul_f32_e32 v167, 0x3f4c422a, v167
	v_add_f32_e32 v167, v167, v167
	v_mul_f32_e32 v167, 0xbfb8aa3b, v167
	v_exp_f32_e32 v167, v167
	v_fmac_f32_e32 v166, v230, v230
	v_add_f32_e32 v167, 1.0, v167
	v_rcp_f32_e32 v167, v167
	s_nop 0
	v_mul_f32_e32 v187, v160, v167
	v_mul_f32_e32 v167, v161, v173
	v_fma_f32 v167, v161, v167, v161
	v_mul_f32_e32 v167, 0x3f4c422a, v167
	v_add_f32_e32 v167, v167, v167
	v_mul_f32_e32 v167, 0xbfb8aa3b, v167
	v_exp_f32_e32 v167, v167
	v_fmac_f32_e32 v166, v187, v187
	v_add_f32_e32 v167, 1.0, v167
	v_rcp_f32_e32 v167, v167
	s_nop 0
	v_mul_f32_e32 v235, v161, v167
	v_mul_f32_e32 v167, v162, v213
	v_fma_f32 v167, v162, v167, v162
	v_mul_f32_e32 v167, 0x3f4c422a, v167
	v_add_f32_e32 v167, v167, v167
	v_mul_f32_e32 v167, 0xbfb8aa3b, v167
	v_exp_f32_e32 v167, v167
	v_fmac_f32_e32 v166, v235, v235
	v_add_f32_e32 v167, 1.0, v167
	v_rcp_f32_e32 v167, v167
	s_nop 0
	v_mul_f32_e32 v233, v162, v167
	v_mul_f32_e32 v167, v163, v205
	v_fma_f32 v167, v163, v167, v163
	v_mul_f32_e32 v167, 0x3f4c422a, v167
	v_add_f32_e32 v167, v167, v167
	v_mul_f32_e32 v167, 0xbfb8aa3b, v167
	v_exp_f32_e32 v167, v167
	v_fmac_f32_e32 v166, v233, v233
	v_add_f32_e32 v167, 1.0, v167
	v_rcp_f32_e32 v167, v167
	s_nop 0
	v_mul_f32_e32 v232, v163, v167
	v_mul_f32_e32 v167, v164, v191
	v_fma_f32 v167, v164, v167, v164
	v_mul_f32_e32 v167, 0x3f4c422a, v167
	v_add_f32_e32 v167, v167, v167
	v_mul_f32_e32 v167, 0xbfb8aa3b, v167
	v_exp_f32_e32 v167, v167
	v_fmac_f32_e32 v166, v232, v232
	v_add_f32_e32 v167, 1.0, v167
	v_rcp_f32_e32 v167, v167
	s_nop 0
	v_mul_f32_e32 v250, v164, v167
	v_mul_f32_e32 v167, v165, v172
	v_fma_f32 v167, v165, v167, v165
	v_mul_f32_e32 v167, 0x3f4c422a, v167
	v_add_f32_e32 v167, v167, v167
	v_mul_f32_e32 v167, 0xbfb8aa3b, v167
	v_exp_f32_e32 v167, v167
	v_fmac_f32_e32 v166, v250, v250
	v_add_f32_e32 v167, 1.0, v167
	v_rcp_f32_e32 v167, v167
	s_nop 0
	v_mul_f32_e32 v249, v165, v167
	v_fmac_f32_e32 v166, v249, v249
	ds_bpermute_b32 v167, v244, v166
	s_waitcnt lgkmcnt(0)
	v_add_f32_e32 v166, v166, v167
	ds_bpermute_b32 v167, v245, v166
	s_waitcnt lgkmcnt(0)
	v_add_f32_e32 v166, v166, v167
	v_fmamk_f32 v166, v166, 0x3c800000, v231
	v_rsq_f32_e32 v251, v166
	v_ashrrev_i32_e32 v166, 7, v210
	v_ashrrev_i32_e32 v167, 31, v166
	v_lshlrev_b64 v[166:167], 16, v[166:167]
	v_lshl_add_u64 v[166:167], s[80:81], 0, v[166:167]
	v_lshl_add_u64 v[166:167], v[166:167], 0, v[168:169]
	v_and_b32_e32 v168, 8, v210
	v_lshlrev_b32_e32 v168, 1, v168
	v_lshl_add_u64 v[166:167], v[166:167], 0, v[168:169]
	v_and_b32_e32 v168, 7, v210
	v_lshlrev_b32_e32 v168, 1, v168
	v_lshl_add_u64 v[166:167], v[166:167], 0, v[168:169]
	s_lshl_b32 s80, s17, 1
	s_mov_b32 s81, s71
	v_lshl_add_u64 v[166:167], v[166:167], 0, s[80:81]
	v_lshlrev_b32_e32 v168, 1, v186
	v_lshl_add_u64 v[170:171], v[166:167], 0, v[168:169]
	ds_read_b128 v[166:169], v193
	v_mul_f32_e32 v211, v211, v251
	s_movk_i32 s17, 0x2000
	s_mov_b64 s[80:81], 0
	s_waitcnt lgkmcnt(0)
	v_mul_f32_e32 v166, v166, v211
	v_cvt_pk_bf16_f32 v166, v166, s0
	global_store_short v[170:171], v166, off
	v_mul_f32_e32 v166, v223, v251
	v_mul_f32_e32 v166, v167, v166
	v_cvt_pk_bf16_f32 v166, v166, s0
	global_store_short v[170:171], v166, off offset:32
	v_mul_f32_e32 v166, v224, v251
	v_mul_f32_e32 v166, v168, v166
	v_cvt_pk_bf16_f32 v166, v166, s0
	global_store_short v[170:171], v166, off offset:64
	v_mul_f32_e32 v166, v225, v251
	v_mul_f32_e32 v166, v169, v166
	v_cvt_pk_bf16_f32 v166, v166, s0
	global_store_short v[170:171], v166, off offset:96
	ds_read_b128 v[166:169], v193 offset:16
	v_mul_f32_e32 v211, v226, v251
	s_waitcnt lgkmcnt(0)
	v_mul_f32_e32 v166, v211, v166
	v_cvt_pk_bf16_f32 v166, v166, s0
	global_store_short v[170:171], v166, off offset:128
	v_mul_f32_e32 v166, v227, v251
	v_mul_f32_e32 v166, v166, v167
	v_cvt_pk_bf16_f32 v166, v166, s0
	global_store_short v[170:171], v166, off offset:160
	v_mul_f32_e32 v166, v228, v251
	v_mul_f32_e32 v166, v166, v168
	v_cvt_pk_bf16_f32 v166, v166, s0
	global_store_short v[170:171], v166, off offset:192
	v_mul_f32_e32 v166, v229, v251
	v_mul_f32_e32 v166, v166, v169
	v_cvt_pk_bf16_f32 v166, v166, s0
	global_store_short v[170:171], v166, off offset:224
	ds_read_b128 v[166:169], v193 offset:128
	v_mul_f32_e32 v211, v248, v251
	v_add_co_u32_e32 v170, vcc, s17, v170
	s_waitcnt lgkmcnt(0)
	v_mul_f32_e32 v166, v211, v166
	v_cvt_pk_bf16_f32 v166, v166, s0
	v_addc_co_u32_e32 v171, vcc, 0, v171, vcc
	global_store_short v[170:171], v166, off
	v_mul_f32_e32 v166, v230, v251
	v_mul_f32_e32 v166, v166, v167
	v_cvt_pk_bf16_f32 v166, v166, s0
	global_store_short v[170:171], v166, off offset:32
	v_mul_f32_e32 v166, v187, v251
	v_mul_f32_e32 v166, v166, v168
	v_cvt_pk_bf16_f32 v166, v166, s0
	global_store_short v[170:171], v166, off offset:64
	v_mul_f32_e32 v166, v235, v251
	v_mul_f32_e32 v166, v166, v169
	v_cvt_pk_bf16_f32 v166, v166, s0
	global_store_short v[170:171], v166, off offset:96
	ds_read_b128 v[166:169], v193 offset:144
	v_mul_f32_e32 v187, v233, v251
	s_waitcnt lgkmcnt(0)
	v_mul_f32_e32 v166, v187, v166
	v_cvt_pk_bf16_f32 v166, v166, s0
	global_store_short v[170:171], v166, off offset:128
	v_mul_f32_e32 v166, v232, v251
	v_mul_f32_e32 v166, v166, v167
	v_cvt_pk_bf16_f32 v166, v166, s0
	global_store_short v[170:171], v166, off offset:160
	v_mul_f32_e32 v166, v250, v251
	v_mul_f32_e32 v166, v166, v168
	v_cvt_pk_bf16_f32 v166, v166, s0
	global_store_short v[170:171], v166, off offset:192
	v_mul_f32_e32 v166, v249, v251
	v_mul_f32_e32 v166, v166, v169
	v_cvt_pk_bf16_f32 v166, v166, s0
	global_store_short v[170:171], v166, off offset:224

.LBB0_234:
	v_add_u32_e32 v210, 0x90, v204
	s_and_b64 vcc, exec, s[14:15]
	ds_read_b32 v162, v243 offset:576
	s_waitcnt lgkmcnt(0)
	s_nop 0
	v_pk_fma_f32 v[148:149], v[80:81], v[162:163], v[144:145] op_sel_hi:[1,0,1]
	v_pk_fma_f32 v[146:147], v[78:79], v[162:163], v[142:143] op_sel_hi:[1,0,1]
	v_pk_fma_f32 v[156:157], v[76:77], v[162:163], v[140:141] op_sel_hi:[1,0,1]
	v_pk_fma_f32 v[154:155], v[74:75], v[162:163], v[138:139] op_sel_hi:[1,0,1]
	v_pk_fma_f32 v[160:161], v[72:73], v[162:163], v[136:137] op_sel_hi:[1,0,1]
	v_pk_fma_f32 v[158:159], v[70:71], v[162:163], v[134:135] op_sel_hi:[1,0,1]
	v_pk_fma_f32 v[164:165], v[68:69], v[162:163], v[132:133] op_sel_hi:[1,0,1]
	v_pk_fma_f32 v[162:163], v[66:67], v[162:163], v[130:131] op_sel_hi:[1,0,1]
	s_cbranch_vccnz .LBB0_330
	s_and_b64 vcc, exec, s[12:13]
	s_mov_b64 s[80:81], -1
	s_cbranch_vccnz .LBB0_253
	v_readlane_b32 s80, v254, 60
	v_readlane_b32 s81, v254, 61
	s_andn2_b64 vcc, exec, s[80:81]
	s_mov_b64 s[80:81], -1
	s_cbranch_vccnz .LBB0_242
	v_readlane_b32 s88, v254, 62
	v_readlane_b32 s89, v254, 63
	s_andn2_b64 vcc, exec, s[88:89]
	v_mul_f32_e32 v222, 0x3d372713, v146
	v_mul_f32_e32 v220, 0x3d372713, v147
	v_mul_f32_e32 v218, 0x3d372713, v148
	v_mul_f32_e32 v216, 0x3d372713, v149
	v_mul_f32_e32 v221, 0x3d372713, v154
	v_mul_f32_e32 v219, 0x3d372713, v155
	v_mul_f32_e32 v217, 0x3d372713, v156
	v_mul_f32_e32 v215, 0x3d372713, v157
	v_mul_f32_e32 v214, 0x3d372713, v158
	v_mul_f32_e32 v212, 0x3d372713, v159
	v_mul_f32_e32 v199, 0x3d372713, v160
	v_mul_f32_e32 v173, 0x3d372713, v161
	v_mul_f32_e32 v213, 0x3d372713, v162
	v_mul_f32_e32 v205, 0x3d372713, v163
	v_mul_f32_e32 v191, 0x3d372713, v164
	v_mul_f32_e32 v172, 0x3d372713, v165
	s_cbranch_vccnz .LBB0_239
	v_mul_f32_e32 v167, v148, v218
	v_fma_f32 v167, v148, v167, v148
	v_mul_f32_e32 v167, 0x3f4c422a, v167
	v_add_f32_e32 v167, v167, v167
	v_mul_f32_e32 v167, 0xbfb8aa3b, v167
	v_exp_f32_e32 v167, v167
	v_mul_f32_e32 v166, v146, v222
	v_fma_f32 v166, v146, v166, v146
	v_mul_f32_e32 v166, 0x3f4c422a, v166
	v_add_f32_e32 v167, 1.0, v167
	v_rcp_f32_e32 v167, v167
	v_add_f32_e32 v166, v166, v166
	v_mul_f32_e32 v166, 0xbfb8aa3b, v166
	v_exp_f32_e32 v166, v166
	v_mul_f32_e32 v224, v148, v167
	v_mul_f32_e32 v167, v149, v216
	v_fma_f32 v167, v149, v167, v149
	v_mul_f32_e32 v167, 0x3f4c422a, v167
	v_add_f32_e32 v167, v167, v167
	v_mul_f32_e32 v167, 0xbfb8aa3b, v167
	v_exp_f32_e32 v167, v167
	v_add_f32_e32 v166, 1.0, v166
	v_rcp_f32_e32 v166, v166
	v_readlane_b32 s80, v255, 0
	v_add_f32_e32 v167, 1.0, v167
	v_rcp_f32_e32 v167, v167
	v_mul_f32_e32 v211, v146, v166
	v_mul_f32_e32 v166, v147, v220
	v_fma_f32 v166, v147, v166, v147
	v_mul_f32_e32 v225, v149, v167
	v_mul_f32_e32 v167, v154, v221
	v_fma_f32 v167, v154, v167, v154
	v_mul_f32_e32 v167, 0x3f4c422a, v167
	v_add_f32_e32 v167, v167, v167
	v_mul_f32_e32 v167, 0xbfb8aa3b, v167
	v_exp_f32_e32 v167, v167
	v_mul_f32_e32 v166, 0x3f4c422a, v166
	v_add_f32_e32 v166, v166, v166
	v_mul_f32_e32 v166, 0xbfb8aa3b, v166
	v_add_f32_e32 v167, 1.0, v167
	v_rcp_f32_e32 v167, v167
	v_exp_f32_e32 v166, v166
	v_readlane_b32 s81, v255, 1
	v_lshlrev_b32_e32 v168, 6, v210
	v_mul_f32_e32 v226, v154, v167
	v_mul_f32_e32 v167, v155, v219
	v_fma_f32 v167, v155, v167, v155
	v_mul_f32_e32 v167, 0x3f4c422a, v167
	v_add_f32_e32 v167, v167, v167
	v_mul_f32_e32 v167, 0xbfb8aa3b, v167
	v_exp_f32_e32 v167, v167
	v_add_f32_e32 v166, 1.0, v166
	v_rcp_f32_e32 v166, v166
	v_and_b32_e32 v168, 0x1c00, v168
	v_add_f32_e32 v167, 1.0, v167
	v_rcp_f32_e32 v167, v167
	v_mul_f32_e32 v223, v147, v166
	v_mul_f32_e32 v166, v223, v223
	v_fmac_f32_e32 v166, v211, v211
	v_mul_f32_e32 v227, v155, v167
	v_mul_f32_e32 v167, v156, v217
	v_fma_f32 v167, v156, v167, v156
	v_mul_f32_e32 v167, 0x3f4c422a, v167
	v_add_f32_e32 v167, v167, v167
	v_mul_f32_e32 v167, 0xbfb8aa3b, v167
	v_exp_f32_e32 v167, v167
	v_fmac_f32_e32 v166, v224, v224
	v_fmac_f32_e32 v166, v225, v225
	v_fmac_f32_e32 v166, v226, v226
	v_add_f32_e32 v167, 1.0, v167
	v_rcp_f32_e32 v167, v167
	v_fmac_f32_e32 v166, v227, v227
	v_mov_b32_e32 v169, v1
	v_readlane_b32 s17, v254, 15
	v_mul_f32_e32 v228, v156, v167
	v_mul_f32_e32 v167, v157, v215
	v_fma_f32 v167, v157, v167, v157
	v_mul_f32_e32 v167, 0x3f4c422a, v167
	v_add_f32_e32 v167, v167, v167
	v_mul_f32_e32 v167, 0xbfb8aa3b, v167
	v_exp_f32_e32 v167, v167
	v_fmac_f32_e32 v166, v228, v228
	v_add_f32_e32 v167, 1.0, v167
	v_rcp_f32_e32 v167, v167
	s_nop 0
	v_mul_f32_e32 v229, v157, v167
	v_mul_f32_e32 v167, v158, v214
	v_fma_f32 v167, v158, v167, v158
	v_mul_f32_e32 v167, 0x3f4c422a, v167
	v_add_f32_e32 v167, v167, v167
	v_mul_f32_e32 v167, 0xbfb8aa3b, v167
	v_exp_f32_e32 v167, v167
	v_fmac_f32_e32 v166, v229, v229
	v_add_f32_e32 v167, 1.0, v167
	v_rcp_f32_e32 v167, v167
	s_nop 0
	v_mul_f32_e32 v248, v158, v167
	v_mul_f32_e32 v167, v159, v212
	v_fma_f32 v167, v159, v167, v159
	v_mul_f32_e32 v167, 0x3f4c422a, v167
	v_add_f32_e32 v167, v167, v167
	v_mul_f32_e32 v167, 0xbfb8aa3b, v167
	v_exp_f32_e32 v167, v167
	v_fmac_f32_e32 v166, v248, v248
	v_add_f32_e32 v167, 1.0, v167
	v_rcp_f32_e32 v167, v167
	s_nop 0
	v_mul_f32_e32 v230, v159, v167
	v_mul_f32_e32 v167, v160, v199
	v_fma_f32 v167, v160, v167, v160
	v_mul_f32_e32 v167, 0x3f4c422a, v167
	v_add_f32_e32 v167, v167, v167
	v_mul_f32_e32 v167, 0xbfb8aa3b, v167
	v_exp_f32_e32 v167, v167
	v_fmac_f32_e32 v166, v230, v230
	v_add_f32_e32 v167, 1.0, v167
	v_rcp_f32_e32 v167, v167
	s_nop 0
	v_mul_f32_e32 v187, v160, v167
	v_mul_f32_e32 v167, v161, v173
	v_fma_f32 v167, v161, v167, v161
	v_mul_f32_e32 v167, 0x3f4c422a, v167
	v_add_f32_e32 v167, v167, v167
	v_mul_f32_e32 v167, 0xbfb8aa3b, v167
	v_exp_f32_e32 v167, v167
	v_fmac_f32_e32 v166, v187, v187
	v_add_f32_e32 v167, 1.0, v167
	v_rcp_f32_e32 v167, v167
	s_nop 0
	v_mul_f32_e32 v235, v161, v167
	v_mul_f32_e32 v167, v162, v213
	v_fma_f32 v167, v162, v167, v162
	v_mul_f32_e32 v167, 0x3f4c422a, v167
	v_add_f32_e32 v167, v167, v167
	v_mul_f32_e32 v167, 0xbfb8aa3b, v167
	v_exp_f32_e32 v167, v167
	v_fmac_f32_e32 v166, v235, v235
	v_add_f32_e32 v167, 1.0, v167
	v_rcp_f32_e32 v167, v167
	s_nop 0
	v_mul_f32_e32 v233, v162, v167
	v_mul_f32_e32 v167, v163, v205
	v_fma_f32 v167, v163, v167, v163
	v_mul_f32_e32 v167, 0x3f4c422a, v167
	v_add_f32_e32 v167, v167, v167
	v_mul_f32_e32 v167, 0xbfb8aa3b, v167
	v_exp_f32_e32 v167, v167
	v_fmac_f32_e32 v166, v233, v233
	v_add_f32_e32 v167, 1.0, v167
	v_rcp_f32_e32 v167, v167
	s_nop 0
	v_mul_f32_e32 v232, v163, v167
	v_mul_f32_e32 v167, v164, v191
	v_fma_f32 v167, v164, v167, v164
	v_mul_f32_e32 v167, 0x3f4c422a, v167
	v_add_f32_e32 v167, v167, v167
	v_mul_f32_e32 v167, 0xbfb8aa3b, v167
	v_exp_f32_e32 v167, v167
	v_fmac_f32_e32 v166, v232, v232
	v_add_f32_e32 v167, 1.0, v167
	v_rcp_f32_e32 v167, v167
	s_nop 0
	v_mul_f32_e32 v250, v164, v167
	v_mul_f32_e32 v167, v165, v172
	v_fma_f32 v167, v165, v167, v165
	v_mul_f32_e32 v167, 0x3f4c422a, v167
	v_add_f32_e32 v167, v167, v167
	v_mul_f32_e32 v167, 0xbfb8aa3b, v167
	v_exp_f32_e32 v167, v167
	v_fmac_f32_e32 v166, v250, v250
	v_add_f32_e32 v167, 1.0, v167
	v_rcp_f32_e32 v167, v167
	s_nop 0
	v_mul_f32_e32 v249, v165, v167
	v_fmac_f32_e32 v166, v249, v249
	ds_bpermute_b32 v167, v244, v166
	s_waitcnt lgkmcnt(0)
	v_add_f32_e32 v166, v166, v167
	ds_bpermute_b32 v167, v245, v166
	s_waitcnt lgkmcnt(0)
	v_add_f32_e32 v166, v166, v167
	v_fmamk_f32 v166, v166, 0x3c800000, v231
	v_rsq_f32_e32 v251, v166
	v_ashrrev_i32_e32 v166, 7, v210
	v_ashrrev_i32_e32 v167, 31, v166
	v_lshlrev_b64 v[166:167], 16, v[166:167]
	v_lshl_add_u64 v[166:167], s[80:81], 0, v[166:167]
	v_lshl_add_u64 v[166:167], v[166:167], 0, v[168:169]
	v_and_b32_e32 v168, 8, v210
	v_lshlrev_b32_e32 v168, 1, v168
	v_lshl_add_u64 v[166:167], v[166:167], 0, v[168:169]
	v_and_b32_e32 v168, 7, v210
	v_lshlrev_b32_e32 v168, 1, v168
	v_lshl_add_u64 v[166:167], v[166:167], 0, v[168:169]
	s_lshl_b32 s80, s17, 1
	s_mov_b32 s81, s71
	v_lshl_add_u64 v[166:167], v[166:167], 0, s[80:81]
	v_lshlrev_b32_e32 v168, 1, v186
	v_lshl_add_u64 v[170:171], v[166:167], 0, v[168:169]
	ds_read_b128 v[166:169], v193
	v_mul_f32_e32 v211, v211, v251
	s_movk_i32 s17, 0x2000
	s_mov_b64 s[80:81], 0
	s_waitcnt lgkmcnt(0)
	v_mul_f32_e32 v166, v166, v211
	v_cvt_pk_bf16_f32 v166, v166, s0
	global_store_short v[170:171], v166, off
	v_mul_f32_e32 v166, v223, v251
	v_mul_f32_e32 v166, v167, v166
	v_cvt_pk_bf16_f32 v166, v166, s0
	global_store_short v[170:171], v166, off offset:32
	v_mul_f32_e32 v166, v224, v251
	v_mul_f32_e32 v166, v168, v166
	v_cvt_pk_bf16_f32 v166, v166, s0
	global_store_short v[170:171], v166, off offset:64
	v_mul_f32_e32 v166, v225, v251
	v_mul_f32_e32 v166, v169, v166
	v_cvt_pk_bf16_f32 v166, v166, s0
	global_store_short v[170:171], v166, off offset:96
	ds_read_b128 v[166:169], v193 offset:16
	v_mul_f32_e32 v211, v226, v251
	s_waitcnt lgkmcnt(0)
	v_mul_f32_e32 v166, v211, v166
	v_cvt_pk_bf16_f32 v166, v166, s0
	global_store_short v[170:171], v166, off offset:128
	v_mul_f32_e32 v166, v227, v251
	v_mul_f32_e32 v166, v166, v167
	v_cvt_pk_bf16_f32 v166, v166, s0
	global_store_short v[170:171], v166, off offset:160
	v_mul_f32_e32 v166, v228, v251
	v_mul_f32_e32 v166, v166, v168
	v_cvt_pk_bf16_f32 v166, v166, s0
	global_store_short v[170:171], v166, off offset:192
	v_mul_f32_e32 v166, v229, v251
	v_mul_f32_e32 v166, v166, v169
	v_cvt_pk_bf16_f32 v166, v166, s0
	global_store_short v[170:171], v166, off offset:224
	ds_read_b128 v[166:169], v193 offset:128
	v_mul_f32_e32 v211, v248, v251
	v_add_co_u32_e32 v170, vcc, s17, v170
	s_waitcnt lgkmcnt(0)
	v_mul_f32_e32 v166, v211, v166
	v_cvt_pk_bf16_f32 v166, v166, s0
	v_addc_co_u32_e32 v171, vcc, 0, v171, vcc
	global_store_short v[170:171], v166, off
	v_mul_f32_e32 v166, v230, v251
	v_mul_f32_e32 v166, v166, v167
	v_cvt_pk_bf16_f32 v166, v166, s0
	global_store_short v[170:171], v166, off offset:32
	v_mul_f32_e32 v166, v187, v251
	v_mul_f32_e32 v166, v166, v168
	v_cvt_pk_bf16_f32 v166, v166, s0
	global_store_short v[170:171], v166, off offset:64
	v_mul_f32_e32 v166, v235, v251
	v_mul_f32_e32 v166, v166, v169
	v_cvt_pk_bf16_f32 v166, v166, s0
	global_store_short v[170:171], v166, off offset:96
	ds_read_b128 v[166:169], v193 offset:144
	v_mul_f32_e32 v187, v233, v251
	s_waitcnt lgkmcnt(0)
	v_mul_f32_e32 v166, v187, v166
	v_cvt_pk_bf16_f32 v166, v166, s0
	global_store_short v[170:171], v166, off offset:128
	v_mul_f32_e32 v166, v232, v251
	v_mul_f32_e32 v166, v166, v167
	v_cvt_pk_bf16_f32 v166, v166, s0
	global_store_short v[170:171], v166, off offset:160
	v_mul_f32_e32 v166, v250, v251
	v_mul_f32_e32 v166, v166, v168
	v_cvt_pk_bf16_f32 v166, v166, s0
	global_store_short v[170:171], v166, off offset:192
	v_mul_f32_e32 v166, v249, v251
	v_mul_f32_e32 v166, v166, v169
	v_cvt_pk_bf16_f32 v166, v166, s0
	global_store_short v[170:171], v166, off offset:224

.LBB0_265:
	v_add_u32_e32 v210, 0xa0, v204
	s_and_b64 vcc, exec, s[14:15]
	ds_read_b32 v162, v243 offset:640
	s_waitcnt lgkmcnt(0)
	s_nop 0
	v_pk_fma_f32 v[152:153], v[64:65], v[162:163], v[144:145] op_sel_hi:[1,0,1]
	v_pk_fma_f32 v[150:151], v[62:63], v[162:163], v[142:143] op_sel_hi:[1,0,1]
	v_pk_fma_f32 v[156:157], v[60:61], v[162:163], v[140:141] op_sel_hi:[1,0,1]
	v_pk_fma_f32 v[154:155], v[58:59], v[162:163], v[138:139] op_sel_hi:[1,0,1]
	v_pk_fma_f32 v[160:161], v[56:57], v[162:163], v[136:137] op_sel_hi:[1,0,1]
	v_pk_fma_f32 v[158:159], v[54:55], v[162:163], v[134:135] op_sel_hi:[1,0,1]
	v_pk_fma_f32 v[164:165], v[52:53], v[162:163], v[132:133] op_sel_hi:[1,0,1]
	v_pk_fma_f32 v[162:163], v[50:51], v[162:163], v[130:131] op_sel_hi:[1,0,1]
	s_cbranch_vccnz .LBB0_331
	s_and_b64 vcc, exec, s[12:13]
	s_mov_b64 s[80:81], -1
	s_cbranch_vccnz .LBB0_284
	v_readlane_b32 s80, v254, 60
	v_readlane_b32 s81, v254, 61
	s_andn2_b64 vcc, exec, s[80:81]
	s_mov_b64 s[80:81], -1
	s_cbranch_vccnz .LBB0_273
	v_readlane_b32 s88, v254, 62
	v_readlane_b32 s89, v254, 63
	s_andn2_b64 vcc, exec, s[88:89]
	v_mul_f32_e32 v220, 0x3d372713, v150
	v_mul_f32_e32 v218, 0x3d372713, v151
	v_mul_f32_e32 v216, 0x3d372713, v152
	v_mul_f32_e32 v214, 0x3d372713, v153
	v_mul_f32_e32 v219, 0x3d372713, v154
	v_mul_f32_e32 v217, 0x3d372713, v155
	v_mul_f32_e32 v215, 0x3d372713, v156
	v_mul_f32_e32 v213, 0x3d372713, v157
	v_mul_f32_e32 v212, 0x3d372713, v158
	v_mul_f32_e32 v208, 0x3d372713, v159
	v_mul_f32_e32 v199, 0x3d372713, v160
	v_mul_f32_e32 v173, 0x3d372713, v161
	v_mul_f32_e32 v209, 0x3d372713, v162
	v_mul_f32_e32 v205, 0x3d372713, v163
	v_mul_f32_e32 v191, 0x3d372713, v164
	v_mul_f32_e32 v172, 0x3d372713, v165
	s_cbranch_vccnz .LBB0_270
	v_mul_f32_e32 v167, v152, v216
	v_fma_f32 v167, v152, v167, v152
	v_mul_f32_e32 v167, 0x3f4c422a, v167
	v_add_f32_e32 v167, v167, v167
	v_mul_f32_e32 v167, 0xbfb8aa3b, v167
	v_exp_f32_e32 v167, v167
	v_mul_f32_e32 v166, v150, v220
	v_fma_f32 v166, v150, v166, v150
	v_mul_f32_e32 v166, 0x3f4c422a, v166
	v_add_f32_e32 v167, 1.0, v167
	v_rcp_f32_e32 v167, v167
	v_add_f32_e32 v166, v166, v166
	v_mul_f32_e32 v166, 0xbfb8aa3b, v166
	v_exp_f32_e32 v166, v166
	v_mul_f32_e32 v222, v152, v167
	v_mul_f32_e32 v167, v153, v214
	v_fma_f32 v167, v153, v167, v153
	v_mul_f32_e32 v167, 0x3f4c422a, v167
	v_add_f32_e32 v167, v167, v167
	v_mul_f32_e32 v167, 0xbfb8aa3b, v167
	v_exp_f32_e32 v167, v167
	v_add_f32_e32 v166, 1.0, v166
	v_rcp_f32_e32 v166, v166
	v_readlane_b32 s80, v255, 0
	v_add_f32_e32 v167, 1.0, v167
	v_rcp_f32_e32 v167, v167
	v_mul_f32_e32 v211, v150, v166
	v_mul_f32_e32 v166, v151, v218
	v_fma_f32 v166, v151, v166, v151
	v_mul_f32_e32 v223, v153, v167
	v_mul_f32_e32 v167, v154, v219
	v_fma_f32 v167, v154, v167, v154
	v_mul_f32_e32 v167, 0x3f4c422a, v167
	v_add_f32_e32 v167, v167, v167
	v_mul_f32_e32 v167, 0xbfb8aa3b, v167
	v_exp_f32_e32 v167, v167
	v_mul_f32_e32 v166, 0x3f4c422a, v166
	v_add_f32_e32 v166, v166, v166
	v_mul_f32_e32 v166, 0xbfb8aa3b, v166
	v_add_f32_e32 v167, 1.0, v167
	v_rcp_f32_e32 v167, v167
	v_exp_f32_e32 v166, v166
	v_readlane_b32 s81, v255, 1
	v_lshlrev_b32_e32 v168, 6, v210
	v_mul_f32_e32 v224, v154, v167
	v_mul_f32_e32 v167, v155, v217
	v_fma_f32 v167, v155, v167, v155
	v_mul_f32_e32 v167, 0x3f4c422a, v167
	v_add_f32_e32 v167, v167, v167
	v_mul_f32_e32 v167, 0xbfb8aa3b, v167
	v_exp_f32_e32 v167, v167
	v_add_f32_e32 v166, 1.0, v166
	v_rcp_f32_e32 v166, v166
	v_and_b32_e32 v168, 0x1c00, v168
	v_add_f32_e32 v167, 1.0, v167
	v_rcp_f32_e32 v167, v167
	v_mul_f32_e32 v221, v151, v166
	v_mul_f32_e32 v166, v221, v221
	v_fmac_f32_e32 v166, v211, v211
	v_mul_f32_e32 v225, v155, v167
	v_mul_f32_e32 v167, v156, v215
	v_fma_f32 v167, v156, v167, v156
	v_mul_f32_e32 v167, 0x3f4c422a, v167
	v_add_f32_e32 v167, v167, v167
	v_mul_f32_e32 v167, 0xbfb8aa3b, v167
	v_exp_f32_e32 v167, v167
	v_fmac_f32_e32 v166, v222, v222
	v_fmac_f32_e32 v166, v223, v223
	v_fmac_f32_e32 v166, v224, v224
	v_add_f32_e32 v167, 1.0, v167
	v_rcp_f32_e32 v167, v167
	v_fmac_f32_e32 v166, v225, v225
	v_mov_b32_e32 v169, v1
	v_readlane_b32 s17, v254, 15
	v_mul_f32_e32 v226, v156, v167
	v_mul_f32_e32 v167, v157, v213
	v_fma_f32 v167, v157, v167, v157
	v_mul_f32_e32 v167, 0x3f4c422a, v167
	v_add_f32_e32 v167, v167, v167
	v_mul_f32_e32 v167, 0xbfb8aa3b, v167
	v_exp_f32_e32 v167, v167
	v_fmac_f32_e32 v166, v226, v226
	v_add_f32_e32 v167, 1.0, v167
	v_rcp_f32_e32 v167, v167
	s_nop 0
	v_mul_f32_e32 v227, v157, v167
	v_mul_f32_e32 v167, v158, v212
	v_fma_f32 v167, v158, v167, v158
	v_mul_f32_e32 v167, 0x3f4c422a, v167
	v_add_f32_e32 v167, v167, v167
	v_mul_f32_e32 v167, 0xbfb8aa3b, v167
	v_exp_f32_e32 v167, v167
	v_fmac_f32_e32 v166, v227, v227
	v_add_f32_e32 v167, 1.0, v167
	v_rcp_f32_e32 v167, v167
	s_nop 0
	v_mul_f32_e32 v228, v158, v167
	v_mul_f32_e32 v167, v159, v208
	v_fma_f32 v167, v159, v167, v159
	v_mul_f32_e32 v167, 0x3f4c422a, v167
	v_add_f32_e32 v167, v167, v167
	v_mul_f32_e32 v167, 0xbfb8aa3b, v167
	v_exp_f32_e32 v167, v167
	v_fmac_f32_e32 v166, v228, v228
	v_add_f32_e32 v167, 1.0, v167
	v_rcp_f32_e32 v167, v167
	s_nop 0
	v_mul_f32_e32 v230, v159, v167
	v_mul_f32_e32 v167, v160, v199
	v_fma_f32 v167, v160, v167, v160
	v_mul_f32_e32 v167, 0x3f4c422a, v167
	v_add_f32_e32 v167, v167, v167
	v_mul_f32_e32 v167, 0xbfb8aa3b, v167
	v_exp_f32_e32 v167, v167
	v_fmac_f32_e32 v166, v230, v230
	v_add_f32_e32 v167, 1.0, v167
	v_rcp_f32_e32 v167, v167
	s_nop 0
	v_mul_f32_e32 v187, v160, v167
	v_mul_f32_e32 v167, v161, v173
	v_fma_f32 v167, v161, v167, v161
	v_mul_f32_e32 v167, 0x3f4c422a, v167
	v_add_f32_e32 v167, v167, v167
	v_mul_f32_e32 v167, 0xbfb8aa3b, v167
	v_exp_f32_e32 v167, v167
	v_fmac_f32_e32 v166, v187, v187
	v_add_f32_e32 v167, 1.0, v167
	v_rcp_f32_e32 v167, v167
	s_nop 0
	v_mul_f32_e32 v235, v161, v167
	v_mul_f32_e32 v167, v162, v209
	v_fma_f32 v167, v162, v167, v162
	v_mul_f32_e32 v167, 0x3f4c422a, v167
	v_add_f32_e32 v167, v167, v167
	v_mul_f32_e32 v167, 0xbfb8aa3b, v167
	v_exp_f32_e32 v167, v167
	v_fmac_f32_e32 v166, v235, v235
	v_add_f32_e32 v167, 1.0, v167
	v_rcp_f32_e32 v167, v167
	s_nop 0
	v_mul_f32_e32 v233, v162, v167
	v_mul_f32_e32 v167, v163, v205
	v_fma_f32 v167, v163, v167, v163
	v_mul_f32_e32 v167, 0x3f4c422a, v167
	v_add_f32_e32 v167, v167, v167
	v_mul_f32_e32 v167, 0xbfb8aa3b, v167
	v_exp_f32_e32 v167, v167
	v_fmac_f32_e32 v166, v233, v233
	v_add_f32_e32 v167, 1.0, v167
	v_rcp_f32_e32 v167, v167
	s_nop 0
	v_mul_f32_e32 v232, v163, v167
	v_mul_f32_e32 v167, v164, v191
	v_fma_f32 v167, v164, v167, v164
	v_mul_f32_e32 v167, 0x3f4c422a, v167
	v_add_f32_e32 v167, v167, v167
	v_mul_f32_e32 v167, 0xbfb8aa3b, v167
	v_exp_f32_e32 v167, v167
	v_fmac_f32_e32 v166, v232, v232
	v_add_f32_e32 v167, 1.0, v167
	v_rcp_f32_e32 v167, v167
	s_nop 0
	v_mul_f32_e32 v248, v164, v167
	v_mul_f32_e32 v167, v165, v172
	v_fma_f32 v167, v165, v167, v165
	v_mul_f32_e32 v167, 0x3f4c422a, v167
	v_add_f32_e32 v167, v167, v167
	v_mul_f32_e32 v167, 0xbfb8aa3b, v167
	v_exp_f32_e32 v167, v167
	v_fmac_f32_e32 v166, v248, v248
	v_add_f32_e32 v167, 1.0, v167
	v_rcp_f32_e32 v167, v167
	s_nop 0
	v_mul_f32_e32 v229, v165, v167
	v_fmac_f32_e32 v166, v229, v229
	ds_bpermute_b32 v167, v244, v166
	s_waitcnt lgkmcnt(0)
	v_add_f32_e32 v166, v166, v167
	ds_bpermute_b32 v167, v245, v166
	s_waitcnt lgkmcnt(0)
	v_add_f32_e32 v166, v166, v167
	v_fmamk_f32 v166, v166, 0x3c800000, v231
	v_rsq_f32_e32 v249, v166
	v_ashrrev_i32_e32 v166, 7, v210
	v_ashrrev_i32_e32 v167, 31, v166
	v_lshlrev_b64 v[166:167], 16, v[166:167]
	v_lshl_add_u64 v[166:167], s[80:81], 0, v[166:167]
	v_lshl_add_u64 v[166:167], v[166:167], 0, v[168:169]
	v_and_b32_e32 v168, 8, v210
	v_lshlrev_b32_e32 v168, 1, v168
	v_lshl_add_u64 v[166:167], v[166:167], 0, v[168:169]
	v_and_b32_e32 v168, 7, v210
	v_lshlrev_b32_e32 v168, 1, v168
	v_lshl_add_u64 v[166:167], v[166:167], 0, v[168:169]
	s_lshl_b32 s80, s17, 1
	s_mov_b32 s81, s71
	v_lshl_add_u64 v[166:167], v[166:167], 0, s[80:81]
	v_lshlrev_b32_e32 v168, 1, v186
	v_lshl_add_u64 v[170:171], v[166:167], 0, v[168:169]
	ds_read_b128 v[166:169], v193
	v_mul_f32_e32 v211, v211, v249
	s_movk_i32 s17, 0x2000
	s_mov_b64 s[80:81], 0
	s_waitcnt lgkmcnt(0)
	v_mul_f32_e32 v166, v166, v211
	v_cvt_pk_bf16_f32 v166, v166, s0
	global_store_short v[170:171], v166, off
	v_mul_f32_e32 v166, v221, v249
	v_mul_f32_e32 v166, v167, v166
	v_cvt_pk_bf16_f32 v166, v166, s0
	global_store_short v[170:171], v166, off offset:32
	v_mul_f32_e32 v166, v222, v249
	v_mul_f32_e32 v166, v168, v166
	v_cvt_pk_bf16_f32 v166, v166, s0
	global_store_short v[170:171], v166, off offset:64
	v_mul_f32_e32 v166, v223, v249
	v_mul_f32_e32 v166, v169, v166
	v_cvt_pk_bf16_f32 v166, v166, s0
	global_store_short v[170:171], v166, off offset:96
	ds_read_b128 v[166:169], v193 offset:16
	v_mul_f32_e32 v211, v224, v249
	s_waitcnt lgkmcnt(0)
	v_mul_f32_e32 v166, v211, v166
	v_cvt_pk_bf16_f32 v166, v166, s0
	global_store_short v[170:171], v166, off offset:128
	v_mul_f32_e32 v166, v225, v249
	v_mul_f32_e32 v166, v166, v167
	v_cvt_pk_bf16_f32 v166, v166, s0
	global_store_short v[170:171], v166, off offset:160
	v_mul_f32_e32 v166, v226, v249
	v_mul_f32_e32 v166, v166, v168
	v_cvt_pk_bf16_f32 v166, v166, s0
	global_store_short v[170:171], v166, off offset:192
	v_mul_f32_e32 v166, v227, v249
	v_mul_f32_e32 v166, v166, v169
	v_cvt_pk_bf16_f32 v166, v166, s0
	global_store_short v[170:171], v166, off offset:224
	ds_read_b128 v[166:169], v193 offset:128
	v_mul_f32_e32 v211, v228, v249
	v_add_co_u32_e32 v170, vcc, s17, v170
	s_waitcnt lgkmcnt(0)
	v_mul_f32_e32 v166, v211, v166
	v_cvt_pk_bf16_f32 v166, v166, s0
	v_addc_co_u32_e32 v171, vcc, 0, v171, vcc
	global_store_short v[170:171], v166, off
	v_mul_f32_e32 v166, v230, v249
	v_mul_f32_e32 v166, v166, v167
	v_cvt_pk_bf16_f32 v166, v166, s0
	global_store_short v[170:171], v166, off offset:32
	v_mul_f32_e32 v166, v187, v249
	v_mul_f32_e32 v166, v166, v168
	v_cvt_pk_bf16_f32 v166, v166, s0
	global_store_short v[170:171], v166, off offset:64
	v_mul_f32_e32 v166, v235, v249
	v_mul_f32_e32 v166, v166, v169
	v_cvt_pk_bf16_f32 v166, v166, s0
	global_store_short v[170:171], v166, off offset:96
	ds_read_b128 v[166:169], v193 offset:144
	v_mul_f32_e32 v187, v233, v249
	s_waitcnt lgkmcnt(0)
	v_mul_f32_e32 v166, v187, v166
	v_cvt_pk_bf16_f32 v166, v166, s0
	global_store_short v[170:171], v166, off offset:128
	v_mul_f32_e32 v166, v232, v249
	v_mul_f32_e32 v166, v166, v167
	v_cvt_pk_bf16_f32 v166, v166, s0
	global_store_short v[170:171], v166, off offset:160
	v_mul_f32_e32 v166, v248, v249
	v_mul_f32_e32 v166, v166, v168
	v_cvt_pk_bf16_f32 v166, v166, s0
	global_store_short v[170:171], v166, off offset:192
	v_mul_f32_e32 v166, v229, v249
	v_mul_f32_e32 v166, v166, v169
	v_cvt_pk_bf16_f32 v166, v166, s0
	global_store_short v[170:171], v166, off offset:224

.LBB0_289:
	s_waitcnt lgkmcnt(0)
	v_add_f32_e32 v166, v166, v167
	v_fmamk_f32 v166, v166, 0x3c800000, v231
	v_rsq_f32_e32 v166, v166
	s_movk_i32 s17, 0x2000
	v_cmp_gt_i32_e32 vcc, s17, v210
	s_and_b64 s[80:81], s[10:11], vcc
	v_mul_f32_e32 v167, 0x3e38aa3b, v166
	v_cndmask_b32_e64 v214, v167, v166, s[10:11]
	v_ashrrev_i32_e32 v166, 8, v210
	v_ashrrev_i32_e32 v167, 31, v166
	v_lshlrev_b64 v[166:167], 20, v[166:167]
	v_readlane_b32 vcc_lo, v254, 27
	v_lshl_add_u64 v[166:167], s[52:53], 0, v[166:167]
	v_readlane_b32 vcc_hi, v254, 28
	s_lshl_b64 s[88:89], s[66:67], 16
	v_lshlrev_b32_e32 v168, 8, v210
	v_lshl_add_u64 v[166:167], v[166:167], 0, vcc
	v_lshl_add_u64 v[166:167], v[166:167], 0, s[88:89]
	v_and_b32_e32 v168, 0xff00, v168
	v_mov_b32_e32 v169, v1
	v_lshl_add_u64 v[212:213], v[166:167], 0, v[168:169]
	ds_read_b128 v[170:173], v192 offset:16
	ds_read_b128 v[166:169], v192
	v_pk_mul_f32 v[216:217], v[150:151], v[214:215] op_sel_hi:[1,0]
	v_pk_mul_f32 v[218:219], v[152:153], v[214:215] op_sel_hi:[1,0]
	s_waitcnt lgkmcnt(0)
	v_pk_mul_f32 v[166:167], v[216:217], v[166:167]
	v_pk_mul_f32 v[168:169], v[218:219], v[168:169]
	v_pk_mul_f32 v[216:217], v[154:155], v[214:215] op_sel_hi:[1,0]
	v_pk_mul_f32 v[218:219], v[156:157], v[214:215] op_sel_hi:[1,0]
	v_pk_mul_f32 v[170:171], v[216:217], v[170:171]
	v_pk_mul_f32 v[172:173], v[218:219], v[172:173]
	v_cvt_pk_bf16_f32 v216, v166, v167
	v_cvt_pk_bf16_f32 v217, v168, v169
	v_cvt_pk_bf16_f32 v218, v170, v171
	v_cvt_pk_bf16_f32 v219, v172, v173
	global_store_dwordx4 v[208:209], v[216:219], off
	s_and_saveexec_b64 s[88:89], s[80:81]
	s_cbranch_execz .LBB0_291
	v_lshl_add_u64 v[216:217], v[212:213], 0, v[0:1]
	global_store_dwordx4 v[216:217], v[166:169], off nt
	global_store_dwordx4 v[216:217], v[170:173], off offset:16 nt
.LBB0_291:
	s_or_b64 exec, exec, s[88:89]
	s_nop 0
	ds_read_b128 v[166:169], v192 offset:128
	s_nop 0
	ds_read_b128 v[170:173], v192 offset:144
	v_mov_b32_e32 v215, v214
	v_mov_b32_e32 v216, v214
	v_mov_b32_e32 v217, v214
	s_and_b64 s[88:89], s[10:11], exec
	v_pk_mul_f32 v[218:219], v[160:161], v[216:217]
	v_pk_mul_f32 v[220:221], v[158:159], v[214:215]
	v_pk_mul_f32 v[216:217], v[164:165], v[216:217]
	v_pk_mul_f32 v[214:215], v[162:163], v[214:215]
	s_mov_b32 s89, s71
	s_cselect_b32 s88, 0x800, 64
	v_lshl_add_u64 v[208:209], v[208:209], 0, s[88:89]
	s_waitcnt lgkmcnt(1)
	v_pk_mul_f32 v[168:169], v[218:219], v[168:169]
	v_pk_mul_f32 v[166:167], v[220:221], v[166:167]
	s_waitcnt lgkmcnt(0)
	v_pk_mul_f32 v[172:173], v[216:217], v[172:173]
	v_pk_mul_f32 v[170:171], v[214:215], v[170:171]
	v_cvt_pk_bf16_f32 v214, v166, v167
	v_cvt_pk_bf16_f32 v215, v168, v169
	v_cvt_pk_bf16_f32 v216, v170, v171
	v_cvt_pk_bf16_f32 v217, v172, v173
	global_store_dwordx4 v[208:209], v[214:217], off
	s_and_saveexec_b64 s[88:89], s[80:81]
	s_cbranch_execz .LBB0_293
	v_lshl_add_u64 v[208:209], v[212:213], 0, v[0:1]
	global_store_dwordx4 v[208:209], v[166:169], off offset:128 nt
	global_store_dwordx4 v[208:209], v[170:173], off offset:144 nt

.LBB0_296:
	s_nop 0
	v_add_u32_e32 v154, 0xb0, v204
	ds_read_b32 v146, v243 offset:704
	s_waitcnt lgkmcnt(0)
	s_and_b64 vcc, exec, s[14:15]
	v_readlane_b32 s80, v254, 51
	v_readlane_b32 s81, v254, 52
	v_pk_fma_f32 v[144:145], v[48:49], v[146:147], v[144:145] op_sel_hi:[1,0,1]
	v_pk_fma_f32 v[142:143], v[46:47], v[146:147], v[142:143] op_sel_hi:[1,0,1]
	v_pk_fma_f32 v[140:141], v[44:45], v[146:147], v[140:141] op_sel_hi:[1,0,1]
	v_pk_fma_f32 v[138:139], v[42:43], v[146:147], v[138:139] op_sel_hi:[1,0,1]
	v_pk_fma_f32 v[136:137], v[40:41], v[146:147], v[136:137] op_sel_hi:[1,0,1]
	v_pk_fma_f32 v[134:135], v[38:39], v[146:147], v[134:135] op_sel_hi:[1,0,1]
	v_pk_fma_f32 v[132:133], v[36:37], v[146:147], v[132:133] op_sel_hi:[1,0,1]
	v_pk_fma_f32 v[130:131], v[34:35], v[146:147], v[130:131] op_sel_hi:[1,0,1]
	s_cbranch_vccnz .LBB0_332
	s_and_b64 vcc, exec, s[12:13]
	s_mov_b64 s[12:13], -1
	s_cbranch_vccnz .LBB0_315
	v_readlane_b32 s12, v254, 60
	v_readlane_b32 s13, v254, 61
	s_andn2_b64 vcc, exec, s[12:13]
	s_mov_b64 s[12:13], -1
	s_cbranch_vccnz .LBB0_304
	v_readlane_b32 s14, v254, 62
	v_readlane_b32 s15, v254, 63
	s_andn2_b64 vcc, exec, s[14:15]
	v_mul_f32_e32 v169, 0x3d372713, v142
	v_mul_f32_e32 v167, 0x3d372713, v143
	v_mul_f32_e32 v165, 0x3d372713, v144
	v_mul_f32_e32 v163, 0x3d372713, v145
	v_mul_f32_e32 v168, 0x3d372713, v138
	v_mul_f32_e32 v166, 0x3d372713, v139
	v_mul_f32_e32 v164, 0x3d372713, v140
	v_mul_f32_e32 v162, 0x3d372713, v141
	v_mul_f32_e32 v161, 0x3d372713, v134
	v_mul_f32_e32 v159, 0x3d372713, v135
	v_mul_f32_e32 v157, 0x3d372713, v136
	v_mul_f32_e32 v153, 0x3d372713, v137
	v_mul_f32_e32 v160, 0x3d372713, v130
	v_mul_f32_e32 v158, 0x3d372713, v131
	v_mul_f32_e32 v156, 0x3d372713, v132
	v_mul_f32_e32 v152, 0x3d372713, v133
	s_cbranch_vccnz .LBB0_301
	v_mul_f32_e32 v147, v144, v165
	v_fma_f32 v147, v144, v147, v144
	v_mul_f32_e32 v147, 0x3f4c422a, v147
	v_add_f32_e32 v147, v147, v147
	v_mul_f32_e32 v147, 0xbfb8aa3b, v147
	v_exp_f32_e32 v147, v147
	v_mul_f32_e32 v146, v142, v169
	v_fma_f32 v146, v142, v146, v142
	v_mul_f32_e32 v146, 0x3f4c422a, v146
	v_add_f32_e32 v147, 1.0, v147
	v_rcp_f32_e32 v147, v147
	v_add_f32_e32 v146, v146, v146
	v_mul_f32_e32 v146, 0xbfb8aa3b, v146
	v_exp_f32_e32 v146, v146
	v_mul_f32_e32 v171, v144, v147
	v_mul_f32_e32 v147, v145, v163
	v_fma_f32 v147, v145, v147, v145
	v_mul_f32_e32 v147, 0x3f4c422a, v147
	v_add_f32_e32 v147, v147, v147
	v_mul_f32_e32 v147, 0xbfb8aa3b, v147
	v_exp_f32_e32 v147, v147
	v_add_f32_e32 v146, 1.0, v146
	v_rcp_f32_e32 v146, v146
	v_readlane_b32 s12, v255, 0
	v_add_f32_e32 v147, 1.0, v147
	v_rcp_f32_e32 v147, v147
	v_mul_f32_e32 v155, v142, v146
	v_mul_f32_e32 v146, v143, v167
	v_fma_f32 v146, v143, v146, v143
	v_mul_f32_e32 v172, v145, v147
	v_mul_f32_e32 v147, v138, v168
	v_fma_f32 v147, v138, v147, v138
	v_mul_f32_e32 v147, 0x3f4c422a, v147
	v_add_f32_e32 v147, v147, v147
	v_mul_f32_e32 v147, 0xbfb8aa3b, v147
	v_exp_f32_e32 v147, v147
	v_mul_f32_e32 v146, 0x3f4c422a, v146
	v_add_f32_e32 v146, v146, v146
	v_mul_f32_e32 v146, 0xbfb8aa3b, v146
	v_add_f32_e32 v147, 1.0, v147
	v_rcp_f32_e32 v147, v147
	v_exp_f32_e32 v146, v146
	v_readlane_b32 s13, v255, 1
	v_lshlrev_b32_e32 v148, 6, v154
	v_mul_f32_e32 v173, v138, v147
	v_mul_f32_e32 v147, v139, v166
	v_fma_f32 v147, v139, v147, v139
	v_mul_f32_e32 v147, 0x3f4c422a, v147
	v_add_f32_e32 v147, v147, v147
	v_mul_f32_e32 v147, 0xbfb8aa3b, v147
	v_exp_f32_e32 v147, v147
	v_add_f32_e32 v146, 1.0, v146
	v_rcp_f32_e32 v146, v146
	v_and_b32_e32 v148, 0x1c00, v148
	v_add_f32_e32 v147, 1.0, v147
	v_rcp_f32_e32 v147, v147
	v_mul_f32_e32 v170, v143, v146
	v_mul_f32_e32 v146, v170, v170
	v_fmac_f32_e32 v146, v155, v155
	v_mul_f32_e32 v191, v139, v147
	v_mul_f32_e32 v147, v140, v164
	v_fma_f32 v147, v140, v147, v140
	v_mul_f32_e32 v147, 0x3f4c422a, v147
	v_add_f32_e32 v147, v147, v147
	v_mul_f32_e32 v147, 0xbfb8aa3b, v147
	v_exp_f32_e32 v147, v147
	v_fmac_f32_e32 v146, v171, v171
	v_fmac_f32_e32 v146, v172, v172
	v_fmac_f32_e32 v146, v173, v173
	v_add_f32_e32 v147, 1.0, v147
	v_rcp_f32_e32 v147, v147
	v_fmac_f32_e32 v146, v191, v191
	v_mov_b32_e32 v149, v1
	v_mul_f32_e32 v199, v140, v147
	v_mul_f32_e32 v147, v141, v162
	v_fma_f32 v147, v141, v147, v141
	v_mul_f32_e32 v147, 0x3f4c422a, v147
	v_add_f32_e32 v147, v147, v147
	v_mul_f32_e32 v147, 0xbfb8aa3b, v147
	v_exp_f32_e32 v147, v147
	v_fmac_f32_e32 v146, v199, v199
	v_add_f32_e32 v147, 1.0, v147
	v_rcp_f32_e32 v147, v147
	s_nop 0
	v_mul_f32_e32 v204, v141, v147
	v_mul_f32_e32 v147, v134, v161
	v_fma_f32 v147, v134, v147, v134
	v_mul_f32_e32 v147, 0x3f4c422a, v147
	v_add_f32_e32 v147, v147, v147
	v_mul_f32_e32 v147, 0xbfb8aa3b, v147
	v_exp_f32_e32 v147, v147
	v_fmac_f32_e32 v146, v204, v204
	v_add_f32_e32 v147, 1.0, v147
	v_rcp_f32_e32 v147, v147
	s_nop 0
	v_mul_f32_e32 v205, v134, v147
	v_mul_f32_e32 v147, v135, v159
	v_fma_f32 v147, v135, v147, v135
	v_mul_f32_e32 v147, 0x3f4c422a, v147
	v_add_f32_e32 v147, v147, v147
	v_mul_f32_e32 v147, 0xbfb8aa3b, v147
	v_exp_f32_e32 v147, v147
	v_fmac_f32_e32 v146, v205, v205
	v_add_f32_e32 v147, 1.0, v147
	v_rcp_f32_e32 v147, v147
	s_nop 0
	v_mul_f32_e32 v212, v135, v147
	v_mul_f32_e32 v147, v136, v157
	v_fma_f32 v147, v136, v147, v136
	v_mul_f32_e32 v147, 0x3f4c422a, v147
	v_add_f32_e32 v147, v147, v147
	v_mul_f32_e32 v147, 0xbfb8aa3b, v147
	v_exp_f32_e32 v147, v147
	v_fmac_f32_e32 v146, v212, v212
	v_add_f32_e32 v147, 1.0, v147
	v_rcp_f32_e32 v147, v147
	s_nop 0
	v_mul_f32_e32 v187, v136, v147
	v_mul_f32_e32 v147, v137, v153
	v_fma_f32 v147, v137, v147, v137
	v_mul_f32_e32 v147, 0x3f4c422a, v147
	v_add_f32_e32 v147, v147, v147
	v_mul_f32_e32 v147, 0xbfb8aa3b, v147
	v_exp_f32_e32 v147, v147
	v_fmac_f32_e32 v146, v187, v187
	v_add_f32_e32 v147, 1.0, v147
	v_rcp_f32_e32 v147, v147
	s_nop 0
	v_mul_f32_e32 v214, v137, v147
	v_mul_f32_e32 v147, v130, v160
	v_fma_f32 v147, v130, v147, v130
	v_mul_f32_e32 v147, 0x3f4c422a, v147
	v_add_f32_e32 v147, v147, v147
	v_mul_f32_e32 v147, 0xbfb8aa3b, v147
	v_exp_f32_e32 v147, v147
	v_fmac_f32_e32 v146, v214, v214
	v_add_f32_e32 v147, 1.0, v147
	v_rcp_f32_e32 v147, v147
	s_nop 0
	v_mul_f32_e32 v213, v130, v147
	v_mul_f32_e32 v147, v131, v158
	v_fma_f32 v147, v131, v147, v131
	v_mul_f32_e32 v147, 0x3f4c422a, v147
	v_add_f32_e32 v147, v147, v147
	v_mul_f32_e32 v147, 0xbfb8aa3b, v147
	v_exp_f32_e32 v147, v147
	v_fmac_f32_e32 v146, v213, v213
	v_add_f32_e32 v147, 1.0, v147
	v_rcp_f32_e32 v147, v147
	s_nop 0
	v_mul_f32_e32 v211, v131, v147
	v_mul_f32_e32 v147, v132, v156
	v_fma_f32 v147, v132, v147, v132
	v_mul_f32_e32 v147, 0x3f4c422a, v147
	v_add_f32_e32 v147, v147, v147
	v_mul_f32_e32 v147, 0xbfb8aa3b, v147
	v_exp_f32_e32 v147, v147
	v_fmac_f32_e32 v146, v211, v211
	v_add_f32_e32 v147, 1.0, v147
	v_rcp_f32_e32 v147, v147
	s_nop 0
	v_mul_f32_e32 v209, v132, v147
	v_mul_f32_e32 v147, v133, v152
	v_fma_f32 v147, v133, v147, v133
	v_mul_f32_e32 v147, 0x3f4c422a, v147
	v_add_f32_e32 v147, v147, v147
	v_mul_f32_e32 v147, 0xbfb8aa3b, v147
	v_exp_f32_e32 v147, v147
	v_fmac_f32_e32 v146, v209, v209
	v_add_f32_e32 v147, 1.0, v147
	v_rcp_f32_e32 v147, v147
	s_nop 0
	v_mul_f32_e32 v208, v133, v147
	v_fmac_f32_e32 v146, v208, v208
	ds_bpermute_b32 v147, v244, v146
	s_waitcnt lgkmcnt(0)
	v_add_f32_e32 v146, v146, v147
	ds_bpermute_b32 v147, v245, v146
	s_waitcnt lgkmcnt(0)
	v_add_f32_e32 v146, v146, v147
	v_fmamk_f32 v146, v146, 0x3c800000, v231
	v_rsq_f32_e32 v210, v146
	v_ashrrev_i32_e32 v146, 7, v154
	v_ashrrev_i32_e32 v147, 31, v146
	v_lshlrev_b64 v[146:147], 16, v[146:147]
	v_lshl_add_u64 v[146:147], s[12:13], 0, v[146:147]
	v_lshl_add_u64 v[146:147], v[146:147], 0, v[148:149]
	v_and_b32_e32 v148, 8, v154
	v_lshlrev_b32_e32 v148, 1, v148
	v_lshl_add_u64 v[146:147], v[146:147], 0, v[148:149]
	v_and_b32_e32 v148, 7, v154
	v_lshlrev_b32_e32 v148, 1, v148
	v_readlane_b32 s12, v254, 15
	v_lshl_add_u64 v[146:147], v[146:147], 0, v[148:149]
	s_lshl_b32 s12, s12, 1
	s_mov_b32 s13, s71
	v_lshl_add_u64 v[146:147], v[146:147], 0, s[12:13]
	v_lshlrev_b32_e32 v148, 1, v186
	v_lshl_add_u64 v[150:151], v[146:147], 0, v[148:149]
	ds_read_b128 v[146:149], v193
	v_mul_f32_e32 v155, v155, v210
	s_movk_i32 s12, 0x2000
	s_waitcnt lgkmcnt(0)
	v_mul_f32_e32 v146, v146, v155
	v_cvt_pk_bf16_f32 v146, v146, s0
	global_store_short v[150:151], v146, off
	v_mul_f32_e32 v146, v170, v210
	v_mul_f32_e32 v146, v147, v146
	v_cvt_pk_bf16_f32 v146, v146, s0
	global_store_short v[150:151], v146, off offset:32
	v_mul_f32_e32 v146, v171, v210
	v_mul_f32_e32 v146, v148, v146
	v_cvt_pk_bf16_f32 v146, v146, s0
	global_store_short v[150:151], v146, off offset:64
	v_mul_f32_e32 v146, v172, v210
	v_mul_f32_e32 v146, v149, v146
	v_cvt_pk_bf16_f32 v146, v146, s0
	global_store_short v[150:151], v146, off offset:96
	ds_read_b128 v[146:149], v193 offset:16
	v_mul_f32_e32 v155, v173, v210
	s_waitcnt lgkmcnt(0)
	v_mul_f32_e32 v146, v155, v146
	v_cvt_pk_bf16_f32 v146, v146, s0
	global_store_short v[150:151], v146, off offset:128
	v_mul_f32_e32 v146, v191, v210
	v_mul_f32_e32 v146, v146, v147
	v_cvt_pk_bf16_f32 v146, v146, s0
	global_store_short v[150:151], v146, off offset:160
	v_mul_f32_e32 v146, v199, v210
	v_mul_f32_e32 v146, v146, v148
	v_cvt_pk_bf16_f32 v146, v146, s0
	global_store_short v[150:151], v146, off offset:192
	v_mul_f32_e32 v146, v204, v210
	v_mul_f32_e32 v146, v146, v149
	v_cvt_pk_bf16_f32 v146, v146, s0
	global_store_short v[150:151], v146, off offset:224
	ds_read_b128 v[146:149], v193 offset:128
	v_mul_f32_e32 v155, v205, v210
	v_add_co_u32_e32 v150, vcc, s12, v150
	s_mov_b64 s[12:13], 0
	s_nop 0
	v_addc_co_u32_e32 v151, vcc, 0, v151, vcc
	s_waitcnt lgkmcnt(0)
	v_mul_f32_e32 v146, v155, v146
	v_cvt_pk_bf16_f32 v146, v146, s0
	global_store_short v[150:151], v146, off
	v_mul_f32_e32 v146, v212, v210
	v_mul_f32_e32 v146, v146, v147
	v_cvt_pk_bf16_f32 v146, v146, s0
	global_store_short v[150:151], v146, off offset:32
	v_mul_f32_e32 v146, v187, v210
	v_mul_f32_e32 v146, v146, v148
	v_cvt_pk_bf16_f32 v146, v146, s0
	global_store_short v[150:151], v146, off offset:64
	v_mul_f32_e32 v146, v214, v210
	v_mul_f32_e32 v146, v146, v149
	v_cvt_pk_bf16_f32 v146, v146, s0
	global_store_short v[150:151], v146, off offset:96
	ds_read_b128 v[146:149], v193 offset:144
	v_mul_f32_e32 v155, v213, v210
	s_waitcnt lgkmcnt(0)
	v_mul_f32_e32 v146, v155, v146
	v_cvt_pk_bf16_f32 v146, v146, s0
	global_store_short v[150:151], v146, off offset:128
	v_mul_f32_e32 v146, v211, v210
	v_mul_f32_e32 v146, v146, v147
	v_cvt_pk_bf16_f32 v146, v146, s0
	global_store_short v[150:151], v146, off offset:160
	v_mul_f32_e32 v146, v209, v210
	v_mul_f32_e32 v146, v146, v148
	v_cvt_pk_bf16_f32 v146, v146, s0
	global_store_short v[150:151], v146, off offset:192
	v_mul_f32_e32 v146, v208, v210
	v_mul_f32_e32 v146, v146, v149
	v_cvt_pk_bf16_f32 v146, v146, s0
	global_store_short v[150:151], v146, off offset:224

.LBB0_320:
	s_waitcnt lgkmcnt(0)
	v_add_f32_e32 v146, v146, v147
	v_fmamk_f32 v146, v146, 0x3c800000, v231
	v_rsq_f32_e32 v146, v146
	s_lshl_b64 s[14:15], s[66:67], 16
	v_lshlrev_b32_e32 v148, 8, v154
	v_and_b32_e32 v148, 0xff00, v148
	v_mul_f32_e32 v147, 0x3e38aa3b, v146
	v_cndmask_b32_e64 v160, v147, v146, s[10:11]
	v_ashrrev_i32_e32 v146, 8, v154
	v_ashrrev_i32_e32 v147, 31, v146
	v_lshlrev_b64 v[146:147], 20, v[146:147]
	v_lshl_add_u64 v[146:147], s[52:53], 0, v[146:147]
	v_readlane_b32 s52, v254, 27
	v_readlane_b32 s53, v254, 28
	v_mov_b32_e32 v149, v1
	v_pk_mul_f32 v[162:163], v[142:143], v[160:161] op_sel_hi:[1,0]
	v_lshl_add_u64 v[146:147], v[146:147], 0, s[52:53]
	v_lshl_add_u64 v[146:147], v[146:147], 0, s[14:15]
	v_lshl_add_u64 v[158:159], v[146:147], 0, v[148:149]
	ds_read_b128 v[150:153], v192 offset:16
	ds_read_b128 v[146:149], v192
	v_pk_mul_f32 v[164:165], v[144:145], v[160:161] op_sel_hi:[1,0]
	s_movk_i32 s12, 0x2000
	v_cmp_gt_i32_e32 vcc, s12, v154
	s_and_b64 s[12:13], s[10:11], vcc
	s_waitcnt lgkmcnt(0)
	v_pk_mul_f32 v[148:149], v[164:165], v[148:149]
	v_pk_mul_f32 v[146:147], v[162:163], v[146:147]
	v_pk_mul_f32 v[162:163], v[138:139], v[160:161] op_sel_hi:[1,0]
	v_pk_mul_f32 v[164:165], v[140:141], v[160:161] op_sel_hi:[1,0]
	v_pk_mul_f32 v[150:151], v[162:163], v[150:151]
	v_pk_mul_f32 v[152:153], v[164:165], v[152:153]
	v_cvt_pk_bf16_f32 v162, v146, v147
	v_cvt_pk_bf16_f32 v163, v148, v149
	v_cvt_pk_bf16_f32 v164, v150, v151
	v_cvt_pk_bf16_f32 v165, v152, v153
	global_store_dwordx4 v[156:157], v[162:165], off
	s_and_saveexec_b64 s[14:15], s[12:13]
	s_cbranch_execz .LBB0_322
	v_lshl_add_u64 v[162:163], v[158:159], 0, v[0:1]
	global_store_dwordx4 v[162:163], v[146:149], off nt
	global_store_dwordx4 v[162:163], v[150:153], off offset:16 nt
.LBB0_322:
	s_or_b64 exec, exec, s[14:15]
	s_nop 0
	ds_read_b128 v[146:149], v192 offset:128
	s_nop 0
	ds_read_b128 v[150:153], v192 offset:144
	v_mov_b32_e32 v161, v160
	v_mov_b32_e32 v162, v160
	v_mov_b32_e32 v163, v160
	s_and_b64 s[10:11], s[10:11], exec
	v_pk_mul_f32 v[164:165], v[136:137], v[162:163]
	v_pk_mul_f32 v[166:167], v[134:135], v[160:161]
	v_pk_mul_f32 v[162:163], v[132:133], v[162:163]
	v_pk_mul_f32 v[160:161], v[130:131], v[160:161]
	s_cselect_b32 s70, 0x800, 64
	v_lshl_add_u64 v[156:157], v[156:157], 0, s[70:71]
	s_waitcnt lgkmcnt(1)
	v_pk_mul_f32 v[148:149], v[164:165], v[148:149]
	v_pk_mul_f32 v[146:147], v[166:167], v[146:147]
	s_waitcnt lgkmcnt(0)
	v_pk_mul_f32 v[152:153], v[162:163], v[152:153]
	v_pk_mul_f32 v[150:151], v[160:161], v[150:151]
	v_cvt_pk_bf16_f32 v160, v146, v147
	v_cvt_pk_bf16_f32 v161, v148, v149
	v_cvt_pk_bf16_f32 v162, v150, v151
	v_cvt_pk_bf16_f32 v163, v152, v153
	global_store_dwordx4 v[156:157], v[160:163], off
	s_and_saveexec_b64 s[10:11], s[12:13]
	s_cbranch_execz .LBB0_324
	v_lshl_add_u64 v[156:157], v[158:159], 0, v[0:1]
	global_store_dwordx4 v[156:157], v[146:149], off offset:128 nt
	global_store_dwordx4 v[156:157], v[150:153], off offset:144 nt
